# v59 plus uniform vmcnt(10) per K-loop phase (deeper LDS-DMA landing window)
# baseline (speedup 1.0000x reference)
.LBB0_262:
	ds_read_b128 v[128:131], v181
	ds_read_b128 v[132:135], v181 offset:1024
	ds_read_b128 v[136:139], v181 offset:2048
	ds_read_b128 v[140:143], v181 offset:3072
	s_add_u32 s6, s4, 0xfff80080
	s_addc_u32 s7, s5, -1
	s_cmp_eq_u32 s37, 28
	s_cselect_b32 s9, s10, s7
	s_cselect_b32 s8, s11, s6
	s_cselect_b32 s7, s20, s36
	s_cselect_b32 s6, s34, s35
	v_lshl_add_u64 v[176:177], s[4:5], 0, v[158:159]
	s_add_i32 m0, s44, 0xc000
	ds_read_b128 v[144:147], v182
	ds_read_b128 v[168:171], v182 offset:1024
	ds_read_b128 v[172:175], v182 offset:2048
	ds_read_b128 v[184:187], v182 offset:3072
	ds_read_b128 v[188:191], v182 offset:4096
	ds_read_b128 v[192:195], v182 offset:5120
	ds_read_b128 v[196:199], v182 offset:6144
	ds_read_b128 v[200:203], v182 offset:7168
	global_load_lds_dwordx4 v[176:177], off
	v_lshl_add_u64 v[176:177], s[4:5], 0, v[160:161]
	s_add_i32 m0, s44, 0xe000
	s_nop 0
	global_load_lds_dwordx4 v[176:177], off
	s_waitcnt lgkmcnt(8)
	s_waitcnt vmcnt(10)
	s_barrier
	s_waitcnt lgkmcnt(0)
	s_waitcnt lgkmcnt(0)
	v_mfma_f32_16x16x32_bf16 v[124:127], v[128:131], v[144:147], v[124:127]
	v_mfma_f32_16x16x32_bf16 v[120:123], v[136:139], v[144:147], v[120:123]
	v_mfma_f32_16x16x32_bf16 v[108:111], v[128:131], v[172:175], v[108:111]
	v_mfma_f32_16x16x32_bf16 v[104:107], v[136:139], v[172:175], v[104:107]
	v_mfma_f32_16x16x32_bf16 v[92:95], v[128:131], v[188:191], v[92:95]
	v_mfma_f32_16x16x32_bf16 v[88:91], v[136:139], v[188:191], v[88:91]
	v_mfma_f32_16x16x32_bf16 v[76:79], v[128:131], v[196:199], v[76:79]
	v_mfma_f32_16x16x32_bf16 v[72:75], v[136:139], v[196:199], v[72:75]
	v_mfma_f32_16x16x32_bf16 v[124:127], v[132:135], v[168:171], v[124:127]
	v_mfma_f32_16x16x32_bf16 v[120:123], v[140:143], v[168:171], v[120:123]
	v_mfma_f32_16x16x32_bf16 v[108:111], v[132:135], v[184:187], v[108:111]
	v_mfma_f32_16x16x32_bf16 v[104:107], v[140:143], v[184:187], v[104:107]
	v_mfma_f32_16x16x32_bf16 v[92:95], v[132:135], v[192:195], v[92:95]
	v_mfma_f32_16x16x32_bf16 v[88:91], v[140:143], v[192:195], v[88:91]
	v_mfma_f32_16x16x32_bf16 v[76:79], v[132:135], v[200:203], v[76:79]
	v_mfma_f32_16x16x32_bf16 v[72:75], v[140:143], v[200:203], v[72:75]
	s_barrier
	s_add_i32 s39, s80, s33
	v_lshl_add_u64 v[176:177], s[6:7], 0, v[150:151]
	s_mov_b32 m0, s39
	ds_read_b128 v[204:207], v183
	ds_read_b128 v[210:213], v183 offset:1024
	ds_read_b128 v[214:217], v183 offset:2048
	ds_read_b128 v[218:221], v183 offset:3072
	global_load_lds_dwordx4 v[176:177], off
	v_lshl_add_u64 v[222:223], s[6:7], 0, v[154:155]
	s_add_i32 m0, s39, 0x2000
	s_nop 0
	global_load_lds_dwordx4 v[222:223], off
	s_waitcnt vmcnt(10)
	s_barrier
	s_waitcnt lgkmcnt(0)
	s_waitcnt lgkmcnt(0)
	v_mfma_f32_16x16x32_bf16 v[116:119], v[204:207], v[144:147], v[116:119]
	v_mfma_f32_16x16x32_bf16 v[112:115], v[214:217], v[144:147], v[112:115]
	v_mfma_f32_16x16x32_bf16 v[100:103], v[204:207], v[172:175], v[100:103]
	v_mfma_f32_16x16x32_bf16 v[96:99], v[214:217], v[172:175], v[96:99]
	v_mfma_f32_16x16x32_bf16 v[84:87], v[204:207], v[188:191], v[84:87]
	v_mfma_f32_16x16x32_bf16 v[80:83], v[214:217], v[188:191], v[80:83]
	v_mfma_f32_16x16x32_bf16 v[68:71], v[204:207], v[196:199], v[68:71]
	v_mfma_f32_16x16x32_bf16 v[64:67], v[214:217], v[196:199], v[64:67]
	v_mfma_f32_16x16x32_bf16 v[116:119], v[210:213], v[168:171], v[116:119]
	v_mfma_f32_16x16x32_bf16 v[112:115], v[218:221], v[168:171], v[112:115]
	v_mfma_f32_16x16x32_bf16 v[100:103], v[210:213], v[184:187], v[100:103]
	v_mfma_f32_16x16x32_bf16 v[96:99], v[218:221], v[184:187], v[96:99]
	v_mfma_f32_16x16x32_bf16 v[84:87], v[210:213], v[192:195], v[84:87]
	v_mfma_f32_16x16x32_bf16 v[80:83], v[218:221], v[192:195], v[80:83]
	v_mfma_f32_16x16x32_bf16 v[68:71], v[210:213], v[200:203], v[68:71]
	v_mfma_f32_16x16x32_bf16 v[64:67], v[218:221], v[200:203], v[64:67]
	s_mov_b32 m0, s44
	v_lshl_add_u64 v[224:225], s[8:9], 0, v[148:149]
	s_barrier
	ds_read_b128 v[144:147], v182 offset:16384
	ds_read_b128 v[168:171], v182 offset:17408
	ds_read_b128 v[172:175], v182 offset:18432
	ds_read_b128 v[184:187], v182 offset:19456
	ds_read_b128 v[188:191], v182 offset:20480
	ds_read_b128 v[192:195], v182 offset:21504
	ds_read_b128 v[196:199], v182 offset:22528
	ds_read_b128 v[200:203], v182 offset:23552
	global_load_lds_dwordx4 v[224:225], off
	v_lshl_add_u64 v[226:227], s[8:9], 0, v[152:153]
	s_mov_b32 m0, s45
	s_nop 0
	global_load_lds_dwordx4 v[226:227], off
	s_waitcnt vmcnt(10)
	s_barrier
	s_waitcnt lgkmcnt(0)
	s_waitcnt lgkmcnt(0)
	v_mfma_f32_16x16x32_bf16 v[60:63], v[128:131], v[144:147], v[60:63]
	v_mfma_f32_16x16x32_bf16 v[56:59], v[136:139], v[144:147], v[56:59]
	v_mfma_f32_16x16x32_bf16 v[44:47], v[128:131], v[172:175], v[44:47]
	v_mfma_f32_16x16x32_bf16 v[40:43], v[136:139], v[172:175], v[40:43]
	v_mfma_f32_16x16x32_bf16 v[28:31], v[128:131], v[188:191], v[28:31]
	v_mfma_f32_16x16x32_bf16 v[24:27], v[136:139], v[188:191], v[24:27]
	v_mfma_f32_16x16x32_bf16 v[12:15], v[128:131], v[196:199], v[12:15]
	v_mfma_f32_16x16x32_bf16 v[8:11], v[136:139], v[196:199], v[8:11]
	v_mfma_f32_16x16x32_bf16 v[60:63], v[132:135], v[168:171], v[60:63]
	v_mfma_f32_16x16x32_bf16 v[56:59], v[140:143], v[168:171], v[56:59]
	v_mfma_f32_16x16x32_bf16 v[44:47], v[132:135], v[184:187], v[44:47]
	v_mfma_f32_16x16x32_bf16 v[40:43], v[140:143], v[184:187], v[40:43]
	v_mfma_f32_16x16x32_bf16 v[28:31], v[132:135], v[192:195], v[28:31]
	v_mfma_f32_16x16x32_bf16 v[24:27], v[140:143], v[192:195], v[24:27]
	v_mfma_f32_16x16x32_bf16 v[12:15], v[132:135], v[200:203], v[12:15]
	v_mfma_f32_16x16x32_bf16 v[8:11], v[140:143], v[200:203], v[8:11]
	s_barrier
	s_add_u32 s78, s6, 0x80000
	s_addc_u32 s79, s7, 0
	s_add_i32 s39, s81, s33
	v_lshl_add_u64 v[128:129], s[78:79], 0, v[150:151]
	s_mov_b32 m0, s39
	s_nop 0
	global_load_lds_dwordx4 v[128:129], off
	v_lshl_add_u64 v[128:129], s[78:79], 0, v[154:155]
	s_add_i32 m0, s39, 0x2000
	s_nop 0
	global_load_lds_dwordx4 v[128:129], off
	s_waitcnt vmcnt(10)
	s_barrier
	v_mfma_f32_16x16x32_bf16 v[52:55], v[204:207], v[144:147], v[52:55]
	v_mfma_f32_16x16x32_bf16 v[48:51], v[214:217], v[144:147], v[48:51]
	v_mfma_f32_16x16x32_bf16 v[36:39], v[204:207], v[172:175], v[36:39]
	v_mfma_f32_16x16x32_bf16 v[32:35], v[214:217], v[172:175], v[32:35]
	v_mfma_f32_16x16x32_bf16 v[20:23], v[204:207], v[188:191], v[20:23]
	v_mfma_f32_16x16x32_bf16 v[16:19], v[214:217], v[188:191], v[16:19]
	v_mfma_f32_16x16x32_bf16 v[4:7], v[204:207], v[196:199], v[4:7]
	v_mfma_f32_16x16x32_bf16 v[0:3], v[214:217], v[196:199], v[0:3]
	v_mfma_f32_16x16x32_bf16 v[52:55], v[210:213], v[168:171], v[52:55]
	v_mfma_f32_16x16x32_bf16 v[48:51], v[218:221], v[168:171], v[48:51]
	v_mfma_f32_16x16x32_bf16 v[36:39], v[210:213], v[184:187], v[36:39]
	v_mfma_f32_16x16x32_bf16 v[32:35], v[218:221], v[184:187], v[32:35]
	v_mfma_f32_16x16x32_bf16 v[20:23], v[210:213], v[192:195], v[20:23]
	v_mfma_f32_16x16x32_bf16 v[16:19], v[218:221], v[192:195], v[16:19]
	v_mfma_f32_16x16x32_bf16 v[4:7], v[210:213], v[200:203], v[4:7]
	v_mfma_f32_16x16x32_bf16 v[0:3], v[218:221], v[200:203], v[0:3]
	s_add_i32 s39, 0, 0x18000
	v_add_u32_e32 v140, s39, v180
	s_barrier
	ds_read_b128 v[128:131], v140
	ds_read_b128 v[132:135], v140 offset:1024
	ds_read_b128 v[136:139], v140 offset:2048
	ds_read_b128 v[140:143], v140 offset:3072
	s_add_u32 s8, s8, 0x80000
	s_addc_u32 s9, s9, 0
	s_mov_b32 m0, s51
	v_lshl_add_u64 v[204:205], s[8:9], 0, v[148:149]
	ds_read_b128 v[144:147], v182 offset:32768
	ds_read_b128 v[168:171], v182 offset:33792
	ds_read_b128 v[172:175], v182 offset:34816
	ds_read_b128 v[184:187], v182 offset:35840
	ds_read_b128 v[188:191], v182 offset:36864
	ds_read_b128 v[192:195], v182 offset:37888
	ds_read_b128 v[196:199], v182 offset:38912
	ds_read_b128 v[200:203], v182 offset:39936
	global_load_lds_dwordx4 v[204:205], off
	v_lshl_add_u64 v[204:205], s[8:9], 0, v[152:153]
	s_mov_b32 m0, s55
	s_nop 0
	global_load_lds_dwordx4 v[204:205], off
	s_waitcnt lgkmcnt(8)
	s_waitcnt vmcnt(10)
	s_barrier
	s_waitcnt lgkmcnt(0)
	s_waitcnt lgkmcnt(0)
	v_mfma_f32_16x16x32_bf16 v[124:127], v[128:131], v[144:147], v[124:127]
	v_mfma_f32_16x16x32_bf16 v[120:123], v[136:139], v[144:147], v[120:123]
	v_mfma_f32_16x16x32_bf16 v[108:111], v[128:131], v[172:175], v[108:111]
	v_mfma_f32_16x16x32_bf16 v[104:107], v[136:139], v[172:175], v[104:107]
	v_mfma_f32_16x16x32_bf16 v[92:95], v[128:131], v[188:191], v[92:95]
	v_mfma_f32_16x16x32_bf16 v[88:91], v[136:139], v[188:191], v[88:91]
	v_mfma_f32_16x16x32_bf16 v[76:79], v[128:131], v[196:199], v[76:79]
	v_mfma_f32_16x16x32_bf16 v[72:75], v[136:139], v[196:199], v[72:75]
	v_mfma_f32_16x16x32_bf16 v[124:127], v[132:135], v[168:171], v[124:127]
	v_mfma_f32_16x16x32_bf16 v[120:123], v[140:143], v[168:171], v[120:123]
	v_mfma_f32_16x16x32_bf16 v[108:111], v[132:135], v[184:187], v[108:111]
	v_mfma_f32_16x16x32_bf16 v[104:107], v[140:143], v[184:187], v[104:107]
	v_mfma_f32_16x16x32_bf16 v[92:95], v[132:135], v[192:195], v[92:95]
	v_mfma_f32_16x16x32_bf16 v[88:91], v[140:143], v[192:195], v[88:91]
	v_mfma_f32_16x16x32_bf16 v[76:79], v[132:135], v[200:203], v[76:79]
	v_mfma_f32_16x16x32_bf16 v[72:75], v[140:143], v[200:203], v[72:75]
	s_barrier
	s_add_i32 s8, 0, 0x1c000
	s_add_i32 s9, s39, s33
	v_add_u32_e32 v156, s8, v180
	v_lshl_add_u64 v[176:177], v[176:177], 0, s[24:25]
	s_mov_b32 m0, s9
	ds_read_b128 v[204:207], v156
	ds_read_b128 v[210:213], v156 offset:1024
	ds_read_b128 v[214:217], v156 offset:2048
	ds_read_b128 v[218:221], v156 offset:3072
	global_load_lds_dwordx4 v[176:177], off
	v_lshl_add_u64 v[176:177], v[222:223], 0, s[24:25]
	s_add_i32 m0, s9, 0x2000
	s_nop 0
	global_load_lds_dwordx4 v[176:177], off
	s_waitcnt vmcnt(10)
	s_barrier
	s_waitcnt lgkmcnt(0)
	s_waitcnt lgkmcnt(0)
	v_mfma_f32_16x16x32_bf16 v[116:119], v[204:207], v[144:147], v[116:119]
	v_mfma_f32_16x16x32_bf16 v[112:115], v[214:217], v[144:147], v[112:115]
	v_mfma_f32_16x16x32_bf16 v[100:103], v[204:207], v[172:175], v[100:103]
	v_mfma_f32_16x16x32_bf16 v[96:99], v[214:217], v[172:175], v[96:99]
	v_mfma_f32_16x16x32_bf16 v[84:87], v[204:207], v[188:191], v[84:87]
	v_mfma_f32_16x16x32_bf16 v[80:83], v[214:217], v[188:191], v[80:83]
	v_mfma_f32_16x16x32_bf16 v[68:71], v[204:207], v[196:199], v[68:71]
	v_mfma_f32_16x16x32_bf16 v[64:67], v[214:217], v[196:199], v[64:67]
	v_mfma_f32_16x16x32_bf16 v[116:119], v[210:213], v[168:171], v[116:119]
	v_mfma_f32_16x16x32_bf16 v[112:115], v[218:221], v[168:171], v[112:115]
	v_mfma_f32_16x16x32_bf16 v[100:103], v[210:213], v[184:187], v[100:103]
	v_mfma_f32_16x16x32_bf16 v[96:99], v[218:221], v[184:187], v[96:99]
	v_mfma_f32_16x16x32_bf16 v[84:87], v[210:213], v[192:195], v[84:87]
	v_mfma_f32_16x16x32_bf16 v[80:83], v[218:221], v[192:195], v[80:83]
	v_mfma_f32_16x16x32_bf16 v[68:71], v[210:213], v[200:203], v[68:71]
	v_mfma_f32_16x16x32_bf16 v[64:67], v[218:221], v[200:203], v[64:67]
	s_mov_b32 m0, s83
	v_lshl_add_u64 v[176:177], v[224:225], 0, s[24:25]
	s_barrier
	ds_read_b128 v[144:147], v182 offset:49152
	ds_read_b128 v[168:171], v182 offset:50176
	ds_read_b128 v[172:175], v182 offset:51200
	ds_read_b128 v[184:187], v182 offset:52224
	ds_read_b128 v[188:191], v182 offset:53248
	ds_read_b128 v[192:195], v182 offset:54272
	ds_read_b128 v[196:199], v182 offset:55296
	ds_read_b128 v[200:203], v182 offset:56320
	global_load_lds_dwordx4 v[176:177], off
	v_lshl_add_u64 v[176:177], v[226:227], 0, s[24:25]
	s_mov_b32 m0, s91
	s_nop 0
	global_load_lds_dwordx4 v[176:177], off
	s_waitcnt vmcnt(10)
	s_barrier
	s_waitcnt lgkmcnt(0)
	s_waitcnt lgkmcnt(0)
	v_mfma_f32_16x16x32_bf16 v[60:63], v[128:131], v[144:147], v[60:63]
	v_mfma_f32_16x16x32_bf16 v[56:59], v[136:139], v[144:147], v[56:59]
	v_mfma_f32_16x16x32_bf16 v[44:47], v[128:131], v[172:175], v[44:47]
	v_mfma_f32_16x16x32_bf16 v[40:43], v[136:139], v[172:175], v[40:43]
	v_mfma_f32_16x16x32_bf16 v[28:31], v[128:131], v[188:191], v[28:31]
	v_mfma_f32_16x16x32_bf16 v[24:27], v[136:139], v[188:191], v[24:27]
	v_mfma_f32_16x16x32_bf16 v[12:15], v[128:131], v[196:199], v[12:15]
	v_mfma_f32_16x16x32_bf16 v[8:11], v[136:139], v[196:199], v[8:11]
	v_mfma_f32_16x16x32_bf16 v[60:63], v[132:135], v[168:171], v[60:63]
	v_mfma_f32_16x16x32_bf16 v[56:59], v[140:143], v[168:171], v[56:59]
	v_mfma_f32_16x16x32_bf16 v[44:47], v[132:135], v[184:187], v[44:47]
	v_mfma_f32_16x16x32_bf16 v[40:43], v[140:143], v[184:187], v[40:43]
	v_mfma_f32_16x16x32_bf16 v[28:31], v[132:135], v[192:195], v[28:31]
	v_mfma_f32_16x16x32_bf16 v[24:27], v[140:143], v[192:195], v[24:27]
	v_mfma_f32_16x16x32_bf16 v[12:15], v[132:135], v[200:203], v[12:15]
	v_mfma_f32_16x16x32_bf16 v[8:11], v[140:143], v[200:203], v[8:11]
	s_barrier
	s_add_u32 s6, s6, 0x80080
	s_addc_u32 s7, s7, 0
	s_add_i32 s8, s8, s33
	v_lshl_add_u64 v[128:129], s[6:7], 0, v[150:151]
	s_mov_b32 m0, s8
	s_nop 0
	global_load_lds_dwordx4 v[128:129], off
	v_lshl_add_u64 v[128:129], s[6:7], 0, v[154:155]
	s_add_i32 m0, s8, 0x2000
	s_nop 0
	global_load_lds_dwordx4 v[128:129], off
	s_waitcnt vmcnt(10)
	s_barrier
	v_mfma_f32_16x16x32_bf16 v[52:55], v[204:207], v[144:147], v[52:55]
	v_mfma_f32_16x16x32_bf16 v[48:51], v[214:217], v[144:147], v[48:51]
	v_mfma_f32_16x16x32_bf16 v[36:39], v[204:207], v[172:175], v[36:39]
	v_mfma_f32_16x16x32_bf16 v[32:35], v[214:217], v[172:175], v[32:35]
	v_mfma_f32_16x16x32_bf16 v[20:23], v[204:207], v[188:191], v[20:23]
	v_mfma_f32_16x16x32_bf16 v[16:19], v[214:217], v[188:191], v[16:19]
	v_mfma_f32_16x16x32_bf16 v[4:7], v[204:207], v[196:199], v[4:7]
	v_mfma_f32_16x16x32_bf16 v[0:3], v[214:217], v[196:199], v[0:3]
	v_mfma_f32_16x16x32_bf16 v[52:55], v[210:213], v[168:171], v[52:55]
	v_mfma_f32_16x16x32_bf16 v[48:51], v[218:221], v[168:171], v[48:51]
	v_mfma_f32_16x16x32_bf16 v[36:39], v[210:213], v[184:187], v[36:39]
	v_mfma_f32_16x16x32_bf16 v[32:35], v[218:221], v[184:187], v[32:35]
	v_mfma_f32_16x16x32_bf16 v[20:23], v[210:213], v[192:195], v[20:23]
	v_mfma_f32_16x16x32_bf16 v[16:19], v[218:221], v[192:195], v[16:19]
	v_mfma_f32_16x16x32_bf16 v[4:7], v[210:213], v[200:203], v[4:7]
	v_mfma_f32_16x16x32_bf16 v[0:3], v[218:221], v[200:203], v[0:3]
	s_add_i32 s37, s37, 2
	s_add_u32 s4, s4, 0x100
	s_addc_u32 s5, s5, 0
	s_add_u32 s35, s35, 0x100
	s_addc_u32 s36, s36, 0
	s_cmp_gt_u32 s37, 29
	s_barrier
	s_cbranch_scc0 .LBB0_262
	v_mov_b32_e32 v185, v179
	v_mov_b32_e32 v184, v178
	s_cmp_lt_i32 s90, 33
	s_mov_b64 s[4:5], -1
	s_cbranch_scc0 .LBB0_589
	s_cmp_gt_i32 s82, 3
	s_cbranch_scc0 .LBB0_586
	s_cmp_gt_u32 s82, 7
	s_cbranch_scc0 .LBB0_551
	s_cmp_gt_u32 s82, 15
	s_cbranch_scc0 .LBB0_548
	s_cmp_gt_u32 s82, 23
	s_cbranch_scc0 .LBB0_545
	s_cmp_gt_u32 s82, 27
	s_cbranch_scc0 .LBB0_486
	s_cmp_gt_u32 s82, 31
	s_cbranch_scc0 .LBB0_315
	s_cmp_gt_u32 s82, 35
	s_cbranch_scc0 .LBB0_280
	s_cmp_gt_u32 s82, 39
	s_cbranch_scc0 .LBB0_277
	s_lshl_b32 s4, s90, 8
	s_add_i32 s4, s4, s57
	v_lshl_add_u32 v128, v185, 3, s59
	v_add_u32_e32 v132, s4, v184
	v_ashrrev_i32_e32 v129, 31, v128
	v_mad_i64_i32 v[130:131], s[4:5], v132, s28, 0
	s_cmp_gt_u32 s82, 41
	s_mov_b64 s[4:5], -1
	v_lshl_add_u64 v[130:131], s[0:1], 0, v[130:131]
	v_lshlrev_b64 v[128:129], 1, v[128:129]
	v_add_u32_e32 v138, 16, v132
	v_add_u32_e32 v137, 32, v132
	v_add_u32_e32 v136, 48, v132
	v_add_u32_e32 v135, 0x80, v132
	v_add_u32_e32 v134, 0x90, v132
	v_add_u32_e32 v133, 0xa0, v132
	v_add_u32_e32 v132, 0xb0, v132
	s_cbranch_scc0 .LBB0_274
	s_lshl_b32 s20, s82, 8
	s_lshl_b64 s[4:5], s[20:21], 1
	v_lshl_add_u64 v[144:145], v[130:131], 0, s[4:5]
	v_cvt_pk_bf16_f32 v140, v124, v125
	v_cvt_pk_bf16_f32 v141, v126, v127
	v_cvt_pk_bf16_f32 v142, v120, v121
	v_cvt_pk_bf16_f32 v143, v122, v123
	v_lshl_add_u64 v[144:145], v[144:145], 0, v[128:129]
	global_store_dwordx4 v[144:145], v[140:143], off
	s_nop 1
	v_cvt_pk_bf16_f32 v140, v116, v117
	v_cvt_pk_bf16_f32 v141, v118, v119
	v_cvt_pk_bf16_f32 v142, v112, v113
	v_cvt_pk_bf16_f32 v143, v114, v115
	global_store_dwordx4 v[144:145], v[140:143], off offset:256
	v_mov_b64_e32 v[144:145], s[0:1]
	v_mad_i64_i32 v[146:147], s[6:7], v138, s28, v[144:145]
	v_lshl_add_u64 v[146:147], v[146:147], 0, s[4:5]
	v_cvt_pk_bf16_f32 v140, v108, v109
	v_cvt_pk_bf16_f32 v141, v110, v111
	v_cvt_pk_bf16_f32 v142, v104, v105
	v_cvt_pk_bf16_f32 v143, v106, v107
	v_lshl_add_u64 v[146:147], v[146:147], 0, v[128:129]
	global_store_dwordx4 v[146:147], v[140:143], off
	s_nop 1
	v_cvt_pk_bf16_f32 v140, v100, v101
	v_cvt_pk_bf16_f32 v141, v102, v103
	v_cvt_pk_bf16_f32 v142, v96, v97
	v_cvt_pk_bf16_f32 v143, v98, v99
	global_store_dwordx4 v[146:147], v[140:143], off offset:256
	v_mad_i64_i32 v[146:147], s[6:7], v137, s28, v[144:145]
	v_lshl_add_u64 v[146:147], v[146:147], 0, s[4:5]
	v_cvt_pk_bf16_f32 v140, v92, v93
	v_cvt_pk_bf16_f32 v141, v94, v95
	v_cvt_pk_bf16_f32 v142, v88, v89
	v_cvt_pk_bf16_f32 v143, v90, v91
	v_lshl_add_u64 v[146:147], v[146:147], 0, v[128:129]
	global_store_dwordx4 v[146:147], v[140:143], off
	s_nop 1
	v_cvt_pk_bf16_f32 v140, v84, v85
	v_cvt_pk_bf16_f32 v141, v86, v87
	v_cvt_pk_bf16_f32 v142, v80, v81
	v_cvt_pk_bf16_f32 v143, v82, v83
	global_store_dwordx4 v[146:147], v[140:143], off offset:256
	v_mad_i64_i32 v[146:147], s[6:7], v136, s28, v[144:145]
	v_lshl_add_u64 v[146:147], v[146:147], 0, s[4:5]
	v_cvt_pk_bf16_f32 v140, v76, v77
	v_cvt_pk_bf16_f32 v141, v78, v79
	v_cvt_pk_bf16_f32 v142, v72, v73
	v_cvt_pk_bf16_f32 v143, v74, v75
	v_lshl_add_u64 v[146:147], v[146:147], 0, v[128:129]
	global_store_dwordx4 v[146:147], v[140:143], off
	s_nop 1
	v_cvt_pk_bf16_f32 v140, v68, v69
	v_cvt_pk_bf16_f32 v141, v70, v71
	v_cvt_pk_bf16_f32 v142, v64, v65
	v_cvt_pk_bf16_f32 v143, v66, v67
	global_store_dwordx4 v[146:147], v[140:143], off offset:256
	v_mad_i64_i32 v[146:147], s[6:7], v135, s28, v[144:145]
	v_lshl_add_u64 v[146:147], v[146:147], 0, s[4:5]
	v_cvt_pk_bf16_f32 v140, v60, v61
	v_cvt_pk_bf16_f32 v141, v62, v63
	v_cvt_pk_bf16_f32 v142, v56, v57
	v_cvt_pk_bf16_f32 v143, v58, v59
	v_lshl_add_u64 v[146:147], v[146:147], 0, v[128:129]
	global_store_dwordx4 v[146:147], v[140:143], off
	s_nop 1
	v_cvt_pk_bf16_f32 v140, v52, v53
	v_cvt_pk_bf16_f32 v141, v54, v55
	v_cvt_pk_bf16_f32 v142, v48, v49
	v_cvt_pk_bf16_f32 v143, v50, v51
	global_store_dwordx4 v[146:147], v[140:143], off offset:256
	v_mad_i64_i32 v[146:147], s[6:7], v134, s28, v[144:145]
	v_lshl_add_u64 v[146:147], v[146:147], 0, s[4:5]
	v_cvt_pk_bf16_f32 v140, v44, v45
	v_cvt_pk_bf16_f32 v141, v46, v47
	v_cvt_pk_bf16_f32 v142, v40, v41
	v_cvt_pk_bf16_f32 v143, v42, v43
	v_lshl_add_u64 v[146:147], v[146:147], 0, v[128:129]
	global_store_dwordx4 v[146:147], v[140:143], off
	s_nop 1
	v_cvt_pk_bf16_f32 v140, v36, v37
	v_cvt_pk_bf16_f32 v141, v38, v39
	v_cvt_pk_bf16_f32 v142, v32, v33
	v_cvt_pk_bf16_f32 v143, v34, v35
	global_store_dwordx4 v[146:147], v[140:143], off offset:256
	v_mad_i64_i32 v[146:147], s[6:7], v133, s28, v[144:145]
	v_lshl_add_u64 v[146:147], v[146:147], 0, s[4:5]
	v_cvt_pk_bf16_f32 v140, v28, v29
	v_cvt_pk_bf16_f32 v141, v30, v31
	v_cvt_pk_bf16_f32 v142, v24, v25
	v_cvt_pk_bf16_f32 v143, v26, v27
	v_lshl_add_u64 v[146:147], v[146:147], 0, v[128:129]
	v_mad_i64_i32 v[144:145], s[6:7], v132, s28, v[144:145]
	global_store_dwordx4 v[146:147], v[140:143], off
	v_lshl_add_u64 v[144:145], v[144:145], 0, s[4:5]
	v_lshl_add_u64 v[144:145], v[144:145], 0, v[128:129]
	v_cvt_pk_bf16_f32 v140, v20, v21
	v_cvt_pk_bf16_f32 v141, v22, v23
	v_cvt_pk_bf16_f32 v142, v16, v17
	v_cvt_pk_bf16_f32 v143, v18, v19
	global_store_dwordx4 v[146:147], v[140:143], off offset:256
	s_mov_b64 s[4:5], 0
	s_nop 0
	v_cvt_pk_bf16_f32 v140, v12, v13
	v_cvt_pk_bf16_f32 v141, v14, v15
	v_cvt_pk_bf16_f32 v142, v8, v9
	v_cvt_pk_bf16_f32 v143, v10, v11
	global_store_dwordx4 v[144:145], v[140:143], off
	s_nop 1
	v_cvt_pk_bf16_f32 v140, v4, v5
	v_cvt_pk_bf16_f32 v141, v6, v7
	v_cvt_pk_bf16_f32 v142, v0, v1
	v_cvt_pk_bf16_f32 v143, v2, v3
	global_store_dwordx4 v[144:145], v[140:143], off offset:256

.LBB0_974:
	ds_read_b128 v[150:153], v147
	ds_read_b128 v[154:157], v147 offset:1024
	ds_read_b128 v[158:161], v147 offset:2048
	ds_read_b128 v[162:165], v147 offset:3072
	s_add_u32 s16, s14, 0x100
	s_addc_u32 s17, s15, 0
	s_cmp_eq_u32 s44, 52
	s_cselect_b32 s21, s3, s17
	s_cselect_b32 s20, s2, s16
	s_cselect_b32 s19, s5, s43
	s_cselect_b32 s18, s4, s42
	v_lshl_add_u64 v[198:199], s[14:15], 0, v[136:137]
	s_add_i32 m0, s24, 0xc000
	ds_read_b128 v[166:169], v148
	ds_read_b128 v[170:173], v148 offset:1024
	ds_read_b128 v[174:177], v148 offset:2048
	ds_read_b128 v[178:181], v148 offset:3072
	ds_read_b128 v[182:185], v148 offset:4096
	ds_read_b128 v[186:189], v148 offset:5120
	ds_read_b128 v[190:193], v148 offset:6144
	ds_read_b128 v[194:197], v148 offset:7168
	global_load_lds_dwordx4 v[198:199], off
	v_lshl_add_u64 v[198:199], s[14:15], 0, v[138:139]
	s_add_i32 m0, s24, 0xe000
	s_nop 0
	global_load_lds_dwordx4 v[198:199], off
	s_waitcnt lgkmcnt(8)
	s_waitcnt vmcnt(10)
	s_barrier
	s_waitcnt lgkmcnt(0)
	s_waitcnt lgkmcnt(0)
	v_mfma_f32_16x16x32_bf16 v[124:127], v[150:153], v[166:169], v[124:127]
	v_mfma_f32_16x16x32_bf16 v[120:123], v[158:161], v[166:169], v[120:123]
	v_mfma_f32_16x16x32_bf16 v[116:119], v[150:153], v[174:177], v[116:119]
	v_mfma_f32_16x16x32_bf16 v[112:115], v[158:161], v[174:177], v[112:115]
	v_mfma_f32_16x16x32_bf16 v[100:103], v[150:153], v[182:185], v[100:103]
	v_mfma_f32_16x16x32_bf16 v[96:99], v[158:161], v[182:185], v[96:99]
	v_mfma_f32_16x16x32_bf16 v[84:87], v[150:153], v[190:193], v[84:87]
	v_mfma_f32_16x16x32_bf16 v[80:83], v[158:161], v[190:193], v[80:83]
	v_mfma_f32_16x16x32_bf16 v[124:127], v[154:157], v[170:173], v[124:127]
	v_mfma_f32_16x16x32_bf16 v[120:123], v[162:165], v[170:173], v[120:123]
	v_mfma_f32_16x16x32_bf16 v[116:119], v[154:157], v[178:181], v[116:119]
	v_mfma_f32_16x16x32_bf16 v[112:115], v[162:165], v[178:181], v[112:115]
	v_mfma_f32_16x16x32_bf16 v[100:103], v[154:157], v[186:189], v[100:103]
	v_mfma_f32_16x16x32_bf16 v[96:99], v[162:165], v[186:189], v[96:99]
	v_mfma_f32_16x16x32_bf16 v[84:87], v[154:157], v[194:197], v[84:87]
	v_mfma_f32_16x16x32_bf16 v[80:83], v[162:165], v[194:197], v[80:83]
	s_barrier
	s_add_i32 s14, s35, s23
	v_lshl_add_u64 v[206:207], s[18:19], 0, v[130:131]
	s_mov_b32 m0, s14
	ds_read_b128 v[198:201], v149
	ds_read_b128 v[202:205], v149 offset:1024
	ds_read_b128 v[210:213], v149 offset:2048
	ds_read_b128 v[214:217], v149 offset:3072
	global_load_lds_dwordx4 v[206:207], off
	v_lshl_add_u64 v[218:219], s[18:19], 0, v[134:135]
	s_add_i32 m0, s14, 0x2000
	s_nop 0
	global_load_lds_dwordx4 v[218:219], off
	s_waitcnt vmcnt(10)
	s_barrier
	s_waitcnt lgkmcnt(0)
	s_waitcnt lgkmcnt(0)
	v_mfma_f32_16x16x32_bf16 v[108:111], v[198:201], v[166:169], v[108:111]
	v_mfma_f32_16x16x32_bf16 v[104:107], v[210:213], v[166:169], v[104:107]
	v_mfma_f32_16x16x32_bf16 v[92:95], v[198:201], v[174:177], v[92:95]
	v_mfma_f32_16x16x32_bf16 v[88:91], v[210:213], v[174:177], v[88:91]
	v_mfma_f32_16x16x32_bf16 v[76:79], v[198:201], v[182:185], v[76:79]
	v_mfma_f32_16x16x32_bf16 v[72:75], v[210:213], v[182:185], v[72:75]
	v_mfma_f32_16x16x32_bf16 v[68:71], v[198:201], v[190:193], v[68:71]
	v_mfma_f32_16x16x32_bf16 v[64:67], v[210:213], v[190:193], v[64:67]
	v_mfma_f32_16x16x32_bf16 v[108:111], v[202:205], v[170:173], v[108:111]
	v_mfma_f32_16x16x32_bf16 v[104:107], v[214:217], v[170:173], v[104:107]
	v_mfma_f32_16x16x32_bf16 v[92:95], v[202:205], v[178:181], v[92:95]
	v_mfma_f32_16x16x32_bf16 v[88:91], v[214:217], v[178:181], v[88:91]
	v_mfma_f32_16x16x32_bf16 v[76:79], v[202:205], v[186:189], v[76:79]
	v_mfma_f32_16x16x32_bf16 v[72:75], v[214:217], v[186:189], v[72:75]
	v_mfma_f32_16x16x32_bf16 v[68:71], v[202:205], v[194:197], v[68:71]
	v_mfma_f32_16x16x32_bf16 v[64:67], v[214:217], v[194:197], v[64:67]
	s_mov_b32 m0, s24
	v_lshl_add_u64 v[220:221], s[20:21], 0, v[128:129]
	s_barrier
	ds_read_b128 v[166:169], v148 offset:16384
	ds_read_b128 v[170:173], v148 offset:17408
	ds_read_b128 v[174:177], v148 offset:18432
	ds_read_b128 v[178:181], v148 offset:19456
	ds_read_b128 v[182:185], v148 offset:20480
	ds_read_b128 v[186:189], v148 offset:21504
	ds_read_b128 v[190:193], v148 offset:22528
	ds_read_b128 v[194:197], v148 offset:23552
	global_load_lds_dwordx4 v[220:221], off
	v_lshl_add_u64 v[222:223], s[20:21], 0, v[132:133]
	s_mov_b32 m0, s25
	s_nop 0
	global_load_lds_dwordx4 v[222:223], off
	s_waitcnt vmcnt(10)
	s_barrier
	s_waitcnt lgkmcnt(0)
	s_waitcnt lgkmcnt(0)
	v_mfma_f32_16x16x32_bf16 v[60:63], v[150:153], v[166:169], v[60:63]
	v_mfma_f32_16x16x32_bf16 v[56:59], v[158:161], v[166:169], v[56:59]
	v_mfma_f32_16x16x32_bf16 v[52:55], v[150:153], v[174:177], v[52:55]
	v_mfma_f32_16x16x32_bf16 v[48:51], v[158:161], v[174:177], v[48:51]
	v_mfma_f32_16x16x32_bf16 v[36:39], v[150:153], v[182:185], v[36:39]
	v_mfma_f32_16x16x32_bf16 v[32:35], v[158:161], v[182:185], v[32:35]
	v_mfma_f32_16x16x32_bf16 v[20:23], v[150:153], v[190:193], v[20:23]
	v_mfma_f32_16x16x32_bf16 v[16:19], v[158:161], v[190:193], v[16:19]
	v_mfma_f32_16x16x32_bf16 v[60:63], v[154:157], v[170:173], v[60:63]
	v_mfma_f32_16x16x32_bf16 v[56:59], v[162:165], v[170:173], v[56:59]
	v_mfma_f32_16x16x32_bf16 v[52:55], v[154:157], v[178:181], v[52:55]
	v_mfma_f32_16x16x32_bf16 v[48:51], v[162:165], v[178:181], v[48:51]
	v_mfma_f32_16x16x32_bf16 v[36:39], v[154:157], v[186:189], v[36:39]
	v_mfma_f32_16x16x32_bf16 v[32:35], v[162:165], v[186:189], v[32:35]
	v_mfma_f32_16x16x32_bf16 v[20:23], v[154:157], v[194:197], v[20:23]
	v_mfma_f32_16x16x32_bf16 v[16:19], v[162:165], v[194:197], v[16:19]
	s_barrier
	s_add_u32 s14, s18, 0xe0000
	s_addc_u32 s15, s19, 0
	s_add_i32 s45, s36, s23
	v_lshl_add_u64 v[150:151], s[14:15], 0, v[130:131]
	s_mov_b32 m0, s45
	s_nop 0
	global_load_lds_dwordx4 v[150:151], off
	v_lshl_add_u64 v[150:151], s[14:15], 0, v[134:135]
	s_add_i32 m0, s45, 0x2000
	s_nop 0
	global_load_lds_dwordx4 v[150:151], off
	s_waitcnt vmcnt(10)
	s_barrier
	v_mfma_f32_16x16x32_bf16 v[44:47], v[198:201], v[166:169], v[44:47]
	v_mfma_f32_16x16x32_bf16 v[40:43], v[210:213], v[166:169], v[40:43]
	v_mfma_f32_16x16x32_bf16 v[28:31], v[198:201], v[174:177], v[28:31]
	v_mfma_f32_16x16x32_bf16 v[24:27], v[210:213], v[174:177], v[24:27]
	v_mfma_f32_16x16x32_bf16 v[12:15], v[198:201], v[182:185], v[12:15]
	v_mfma_f32_16x16x32_bf16 v[8:11], v[210:213], v[182:185], v[8:11]
	v_mfma_f32_16x16x32_bf16 v[4:7], v[198:201], v[190:193], v[4:7]
	v_mfma_f32_16x16x32_bf16 v[0:3], v[210:213], v[190:193], v[0:3]
	v_mfma_f32_16x16x32_bf16 v[44:47], v[202:205], v[170:173], v[44:47]
	v_mfma_f32_16x16x32_bf16 v[40:43], v[214:217], v[170:173], v[40:43]
	v_mfma_f32_16x16x32_bf16 v[28:31], v[202:205], v[178:181], v[28:31]
	v_mfma_f32_16x16x32_bf16 v[24:27], v[214:217], v[178:181], v[24:27]
	v_mfma_f32_16x16x32_bf16 v[12:15], v[202:205], v[186:189], v[12:15]
	v_mfma_f32_16x16x32_bf16 v[8:11], v[214:217], v[186:189], v[8:11]
	v_mfma_f32_16x16x32_bf16 v[4:7], v[202:205], v[194:197], v[4:7]
	v_mfma_f32_16x16x32_bf16 v[0:3], v[214:217], v[194:197], v[0:3]
	s_add_i32 s45, 0, 0x18000
	v_add_u32_e32 v162, s45, v146
	s_barrier
	ds_read_b128 v[150:153], v162
	ds_read_b128 v[154:157], v162 offset:1024
	ds_read_b128 v[158:161], v162 offset:2048
	ds_read_b128 v[162:165], v162 offset:3072
	s_add_u32 s14, s20, 0xe0000
	s_addc_u32 s15, s21, 0
	s_mov_b32 m0, s26
	v_lshl_add_u64 v[198:199], s[14:15], 0, v[128:129]
	ds_read_b128 v[166:169], v148 offset:32768
	ds_read_b128 v[170:173], v148 offset:33792
	ds_read_b128 v[174:177], v148 offset:34816
	ds_read_b128 v[178:181], v148 offset:35840
	ds_read_b128 v[182:185], v148 offset:36864
	ds_read_b128 v[186:189], v148 offset:37888
	ds_read_b128 v[190:193], v148 offset:38912
	ds_read_b128 v[194:197], v148 offset:39936
	global_load_lds_dwordx4 v[198:199], off
	v_lshl_add_u64 v[198:199], s[14:15], 0, v[132:133]
	s_mov_b32 m0, s27
	s_nop 0
	global_load_lds_dwordx4 v[198:199], off
	s_waitcnt lgkmcnt(8)
	s_waitcnt vmcnt(10)
	s_barrier
	s_waitcnt lgkmcnt(0)
	s_waitcnt lgkmcnt(0)
	v_mfma_f32_16x16x32_bf16 v[124:127], v[150:153], v[166:169], v[124:127]
	v_mfma_f32_16x16x32_bf16 v[120:123], v[158:161], v[166:169], v[120:123]
	v_mfma_f32_16x16x32_bf16 v[116:119], v[150:153], v[174:177], v[116:119]
	v_mfma_f32_16x16x32_bf16 v[112:115], v[158:161], v[174:177], v[112:115]
	v_mfma_f32_16x16x32_bf16 v[100:103], v[150:153], v[182:185], v[100:103]
	v_mfma_f32_16x16x32_bf16 v[96:99], v[158:161], v[182:185], v[96:99]
	v_mfma_f32_16x16x32_bf16 v[84:87], v[150:153], v[190:193], v[84:87]
	v_mfma_f32_16x16x32_bf16 v[80:83], v[158:161], v[190:193], v[80:83]
	v_mfma_f32_16x16x32_bf16 v[124:127], v[154:157], v[170:173], v[124:127]
	v_mfma_f32_16x16x32_bf16 v[120:123], v[162:165], v[170:173], v[120:123]
	v_mfma_f32_16x16x32_bf16 v[116:119], v[154:157], v[178:181], v[116:119]
	v_mfma_f32_16x16x32_bf16 v[112:115], v[162:165], v[178:181], v[112:115]
	v_mfma_f32_16x16x32_bf16 v[100:103], v[154:157], v[186:189], v[100:103]
	v_mfma_f32_16x16x32_bf16 v[96:99], v[162:165], v[186:189], v[96:99]
	v_mfma_f32_16x16x32_bf16 v[84:87], v[154:157], v[194:197], v[84:87]
	v_mfma_f32_16x16x32_bf16 v[80:83], v[162:165], v[194:197], v[80:83]
	s_barrier
	s_add_i32 s20, 0, 0x1c000
	s_add_i32 s14, s45, s23
	v_add_u32_e32 v214, s20, v146
	v_lshl_add_u64 v[206:207], v[206:207], 0, s[8:9]
	s_mov_b32 m0, s14
	ds_read_b128 v[198:201], v214
	ds_read_b128 v[202:205], v214 offset:1024
	ds_read_b128 v[210:213], v214 offset:2048
	ds_read_b128 v[214:217], v214 offset:3072
	global_load_lds_dwordx4 v[206:207], off
	v_lshl_add_u64 v[206:207], v[218:219], 0, s[8:9]
	s_add_i32 m0, s14, 0x2000
	s_nop 0
	global_load_lds_dwordx4 v[206:207], off
	s_waitcnt vmcnt(10)
	s_barrier
	s_waitcnt lgkmcnt(0)
	s_waitcnt lgkmcnt(0)
	v_mfma_f32_16x16x32_bf16 v[108:111], v[198:201], v[166:169], v[108:111]
	v_mfma_f32_16x16x32_bf16 v[104:107], v[210:213], v[166:169], v[104:107]
	v_mfma_f32_16x16x32_bf16 v[92:95], v[198:201], v[174:177], v[92:95]
	v_mfma_f32_16x16x32_bf16 v[88:91], v[210:213], v[174:177], v[88:91]
	v_mfma_f32_16x16x32_bf16 v[76:79], v[198:201], v[182:185], v[76:79]
	v_mfma_f32_16x16x32_bf16 v[72:75], v[210:213], v[182:185], v[72:75]
	v_mfma_f32_16x16x32_bf16 v[68:71], v[198:201], v[190:193], v[68:71]
	v_mfma_f32_16x16x32_bf16 v[64:67], v[210:213], v[190:193], v[64:67]
	v_mfma_f32_16x16x32_bf16 v[108:111], v[202:205], v[170:173], v[108:111]
	v_mfma_f32_16x16x32_bf16 v[104:107], v[214:217], v[170:173], v[104:107]
	v_mfma_f32_16x16x32_bf16 v[92:95], v[202:205], v[178:181], v[92:95]
	v_mfma_f32_16x16x32_bf16 v[88:91], v[214:217], v[178:181], v[88:91]
	v_mfma_f32_16x16x32_bf16 v[76:79], v[202:205], v[186:189], v[76:79]
	v_mfma_f32_16x16x32_bf16 v[72:75], v[214:217], v[186:189], v[72:75]
	v_mfma_f32_16x16x32_bf16 v[68:71], v[202:205], v[194:197], v[68:71]
	v_mfma_f32_16x16x32_bf16 v[64:67], v[214:217], v[194:197], v[64:67]
	s_mov_b32 m0, s31
	v_lshl_add_u64 v[206:207], v[220:221], 0, s[8:9]
	s_barrier
	ds_read_b128 v[166:169], v148 offset:49152
	ds_read_b128 v[170:173], v148 offset:50176
	ds_read_b128 v[174:177], v148 offset:51200
	ds_read_b128 v[178:181], v148 offset:52224
	ds_read_b128 v[182:185], v148 offset:53248
	ds_read_b128 v[186:189], v148 offset:54272
	ds_read_b128 v[190:193], v148 offset:55296
	ds_read_b128 v[194:197], v148 offset:56320
	global_load_lds_dwordx4 v[206:207], off
	v_lshl_add_u64 v[206:207], v[222:223], 0, s[8:9]
	s_mov_b32 m0, s33
	s_nop 0
	global_load_lds_dwordx4 v[206:207], off
	s_waitcnt vmcnt(10)
	s_barrier
	s_waitcnt lgkmcnt(0)
	s_waitcnt lgkmcnt(0)
	v_mfma_f32_16x16x32_bf16 v[60:63], v[150:153], v[166:169], v[60:63]
	v_mfma_f32_16x16x32_bf16 v[56:59], v[158:161], v[166:169], v[56:59]
	v_mfma_f32_16x16x32_bf16 v[52:55], v[150:153], v[174:177], v[52:55]
	v_mfma_f32_16x16x32_bf16 v[48:51], v[158:161], v[174:177], v[48:51]
	v_mfma_f32_16x16x32_bf16 v[36:39], v[150:153], v[182:185], v[36:39]
	v_mfma_f32_16x16x32_bf16 v[32:35], v[158:161], v[182:185], v[32:35]
	v_mfma_f32_16x16x32_bf16 v[20:23], v[150:153], v[190:193], v[20:23]
	v_mfma_f32_16x16x32_bf16 v[16:19], v[158:161], v[190:193], v[16:19]
	v_mfma_f32_16x16x32_bf16 v[60:63], v[154:157], v[170:173], v[60:63]
	v_mfma_f32_16x16x32_bf16 v[56:59], v[162:165], v[170:173], v[56:59]
	v_mfma_f32_16x16x32_bf16 v[52:55], v[154:157], v[178:181], v[52:55]
	v_mfma_f32_16x16x32_bf16 v[48:51], v[162:165], v[178:181], v[48:51]
	v_mfma_f32_16x16x32_bf16 v[36:39], v[154:157], v[186:189], v[36:39]
	v_mfma_f32_16x16x32_bf16 v[32:35], v[162:165], v[186:189], v[32:35]
	v_mfma_f32_16x16x32_bf16 v[20:23], v[154:157], v[194:197], v[20:23]
	v_mfma_f32_16x16x32_bf16 v[16:19], v[162:165], v[194:197], v[16:19]
	s_barrier
	s_add_u32 s14, s18, 0xe0080
	s_addc_u32 s15, s19, 0
	s_add_i32 s18, s20, s23
	v_lshl_add_u64 v[150:151], s[14:15], 0, v[130:131]
	s_mov_b32 m0, s18
	s_nop 0
	global_load_lds_dwordx4 v[150:151], off
	v_lshl_add_u64 v[150:151], s[14:15], 0, v[134:135]
	s_add_i32 m0, s18, 0x2000
	s_nop 0
	global_load_lds_dwordx4 v[150:151], off
	s_waitcnt vmcnt(10)
	s_barrier
	v_mfma_f32_16x16x32_bf16 v[44:47], v[198:201], v[166:169], v[44:47]
	v_mfma_f32_16x16x32_bf16 v[40:43], v[210:213], v[166:169], v[40:43]
	v_mfma_f32_16x16x32_bf16 v[28:31], v[198:201], v[174:177], v[28:31]
	v_mfma_f32_16x16x32_bf16 v[24:27], v[210:213], v[174:177], v[24:27]
	v_mfma_f32_16x16x32_bf16 v[12:15], v[198:201], v[182:185], v[12:15]
	v_mfma_f32_16x16x32_bf16 v[8:11], v[210:213], v[182:185], v[8:11]
	v_mfma_f32_16x16x32_bf16 v[4:7], v[198:201], v[190:193], v[4:7]
	v_mfma_f32_16x16x32_bf16 v[0:3], v[210:213], v[190:193], v[0:3]
	v_mfma_f32_16x16x32_bf16 v[44:47], v[202:205], v[170:173], v[44:47]
	v_mfma_f32_16x16x32_bf16 v[40:43], v[214:217], v[170:173], v[40:43]
	v_mfma_f32_16x16x32_bf16 v[28:31], v[202:205], v[178:181], v[28:31]
	v_mfma_f32_16x16x32_bf16 v[24:27], v[214:217], v[178:181], v[24:27]
	v_mfma_f32_16x16x32_bf16 v[12:15], v[202:205], v[186:189], v[12:15]
	v_mfma_f32_16x16x32_bf16 v[8:11], v[214:217], v[186:189], v[8:11]
	v_mfma_f32_16x16x32_bf16 v[4:7], v[202:205], v[194:197], v[4:7]
	v_mfma_f32_16x16x32_bf16 v[0:3], v[214:217], v[194:197], v[0:3]
	s_add_i32 s44, s44, 2
	s_add_u32 s42, s42, 0x100
	s_addc_u32 s43, s43, 0
	s_cmp_gt_u32 s44, 53
	s_mov_b64 s[14:15], s[16:17]
	s_barrier
	s_cbranch_scc0 .LBB0_974
	v_mov_b32_e32 v150, v145
	v_mov_b32_e32 v151, v144
	s_lshl_b32 s14, s34, 8
	s_add_i32 s14, s14, s29
	v_add_u32_e32 v150, s14, v150
	s_lshl_b32 s14, s41, 8
	s_or_b32 s14, s14, s30
	v_lshl_add_u32 v152, v151, 3, s14
	v_ashrrev_i32_e32 v151, 31, v150
	v_lshlrev_b64 v[150:151], 12, v[150:151]
	v_ashrrev_i32_e32 v153, 31, v152
	v_lshl_add_u64 v[150:151], s[10:11], 0, v[150:151]
	v_lshl_add_u64 v[150:151], v[152:153], 1, v[150:151]
	v_cvt_pk_bf16_f32 v108, v108, v109
	v_cvt_pk_bf16_f32 v109, v110, v111
	v_cvt_pk_bf16_f32 v110, v104, v105
	v_cvt_pk_bf16_f32 v111, v106, v107
	s_mov_b64 s[14:15], 0x10000
	global_store_dwordx4 v[150:151], v[108:111], off offset:256
	v_cvt_pk_bf16_f32 v92, v92, v93
	v_cvt_pk_bf16_f32 v93, v94, v95
	v_lshl_add_u64 v[108:109], v[150:151], 0, s[14:15]
	s_mov_b32 s14, 0x10000
	v_add_co_u32_e32 v110, vcc, s14, v150
	v_cvt_pk_bf16_f32 v94, v88, v89
	v_cvt_pk_bf16_f32 v95, v90, v91
	s_mov_b64 s[14:15], 0x20000
	v_addc_co_u32_e32 v111, vcc, 0, v151, vcc
	global_store_dwordx4 v[108:109], v[92:95], off offset:256
	v_cvt_pk_bf16_f32 v76, v76, v77
	v_cvt_pk_bf16_f32 v77, v78, v79
	v_lshl_add_u64 v[92:93], v[150:151], 0, s[14:15]
	s_mov_b32 s14, 0x20000
	v_add_co_u32_e32 v94, vcc, s14, v150
	v_cvt_pk_bf16_f32 v78, v72, v73
	v_cvt_pk_bf16_f32 v79, v74, v75
	s_mov_b64 s[14:15], 0x30000
	v_addc_co_u32_e32 v95, vcc, 0, v151, vcc
	global_store_dwordx4 v[92:93], v[76:79], off offset:256
	v_cvt_pk_bf16_f32 v68, v68, v69
	v_cvt_pk_bf16_f32 v69, v70, v71
	v_lshl_add_u64 v[76:77], v[150:151], 0, s[14:15]
	s_mov_b32 s14, 0x30000
	v_add_co_u32_e32 v78, vcc, s14, v150
	s_mov_b64 s[14:15], 0x80000
	s_nop 0
	v_addc_co_u32_e32 v79, vcc, 0, v151, vcc
	v_cvt_pk_bf16_f32 v70, v64, v65
	v_lshl_add_u64 v[64:65], v[150:151], 0, s[14:15]
	s_mov_b32 s14, 0x80000
	v_cvt_pk_bf16_f32 v60, v60, v61
	v_cvt_pk_bf16_f32 v61, v62, v63
	v_cvt_pk_bf16_f32 v62, v56, v57
	v_add_co_u32_e32 v56, vcc, s14, v150
	v_cvt_pk_bf16_f32 v44, v44, v45
	v_cvt_pk_bf16_f32 v45, v46, v47
	v_cvt_pk_bf16_f32 v46, v40, v41
	v_cvt_pk_bf16_f32 v47, v42, v43
	s_mov_b64 s[14:15], 0x90000
	v_addc_co_u32_e32 v57, vcc, 0, v151, vcc
	global_store_dwordx4 v[64:65], v[44:47], off offset:256
	v_cvt_pk_bf16_f32 v28, v28, v29
	v_cvt_pk_bf16_f32 v29, v30, v31
	v_lshl_add_u64 v[44:45], v[150:151], 0, s[14:15]
	s_mov_b32 s14, 0x90000
	v_add_co_u32_e32 v46, vcc, s14, v150
	v_cvt_pk_bf16_f32 v30, v24, v25
	s_nop 0
	v_addc_co_u32_e32 v47, vcc, 0, v151, vcc
	v_cvt_pk_bf16_f32 v31, v26, v27
	global_store_dwordx4 v[44:45], v[28:31], off offset:256
	s_mov_b64 s[14:15], 0xa0000
	v_cvt_pk_bf16_f32 v12, v12, v13
	v_add_co_u32_e32 v30, vcc, s37, v150
	v_lshl_add_u64 v[28:29], v[150:151], 0, s[14:15]
	s_nop 0
	v_addc_co_u32_e32 v31, vcc, 0, v151, vcc
	v_cvt_pk_bf16_f32 v13, v14, v15
	v_cvt_pk_bf16_f32 v14, v8, v9
	v_cvt_pk_bf16_f32 v15, v10, v11
	global_store_dwordx4 v[28:29], v[12:15], off offset:256
	v_cvt_pk_bf16_f32 v124, v124, v125
	v_cvt_pk_bf16_f32 v125, v126, v127
	v_add_co_u32_e32 v14, vcc, s38, v150
	v_cvt_pk_bf16_f32 v126, v120, v121
	s_nop 0
	v_addc_co_u32_e32 v15, vcc, 0, v151, vcc
	v_cvt_pk_bf16_f32 v127, v122, v123
	v_cvt_pk_bf16_f32 v104, v116, v117
	v_cvt_pk_bf16_f32 v105, v118, v119
	v_cvt_pk_bf16_f32 v106, v112, v113
	v_cvt_pk_bf16_f32 v107, v114, v115
	v_cvt_pk_bf16_f32 v88, v100, v101
	v_cvt_pk_bf16_f32 v89, v102, v103
	v_cvt_pk_bf16_f32 v90, v96, v97
	v_cvt_pk_bf16_f32 v91, v98, v99
	v_cvt_pk_bf16_f32 v72, v84, v85
	v_cvt_pk_bf16_f32 v73, v86, v87
	v_cvt_pk_bf16_f32 v74, v80, v81
	v_cvt_pk_bf16_f32 v75, v82, v83
	v_cvt_pk_bf16_f32 v71, v66, v67
	v_cvt_pk_bf16_f32 v63, v58, v59
	v_cvt_pk_bf16_f32 v40, v52, v53
	v_cvt_pk_bf16_f32 v41, v54, v55
	v_cvt_pk_bf16_f32 v42, v48, v49
	v_cvt_pk_bf16_f32 v43, v50, v51
	v_cvt_pk_bf16_f32 v24, v36, v37
	v_cvt_pk_bf16_f32 v25, v38, v39
	v_cvt_pk_bf16_f32 v26, v32, v33
	v_cvt_pk_bf16_f32 v27, v34, v35
	v_lshl_add_u64 v[12:13], v[150:151], 0, s[12:13]
	v_cvt_pk_bf16_f32 v8, v20, v21
	v_cvt_pk_bf16_f32 v9, v22, v23
	v_cvt_pk_bf16_f32 v10, v16, v17
	v_cvt_pk_bf16_f32 v11, v18, v19
	v_cvt_pk_bf16_f32 v4, v4, v5
	v_cvt_pk_bf16_f32 v5, v6, v7
	v_cvt_pk_bf16_f32 v6, v0, v1
	v_cvt_pk_bf16_f32 v7, v2, v3
	s_and_b64 vcc, exec, s[0:1]
	s_mov_b32 s41, s39
	s_mov_b32 s34, s40
	s_mov_b64 s[16:17], s[4:5]
	s_mov_b64 s[14:15], s[2:3]
	global_store_dwordx4 v[150:151], v[124:127], off
	global_store_dwordx4 v[110:111], v[104:107], off
	global_store_dwordx4 v[94:95], v[88:91], off
	global_store_dwordx4 v[78:79], v[72:75], off
	global_store_dwordx4 v[76:77], v[68:71], off offset:256
	global_store_dwordx4 v[56:57], v[60:63], off
	global_store_dwordx4 v[46:47], v[40:43], off
	global_store_dwordx4 v[30:31], v[24:27], off
	global_store_dwordx4 v[14:15], v[8:11], off
	global_store_dwordx4 v[12:13], v[4:7], off offset:256
	s_cbranch_vccz .LBB0_963
	s_waitcnt vmcnt(0)
	s_cmpk_gt_u32 s22, 0xff
	s_cbranch_scc1 .LBB0_978
	s_barrier

.LBB0_1200:
	s_waitcnt lgkmcnt(0)
	ds_read_b128 v[144:147], v151
	ds_read_b128 v[156:159], v151 offset:1024
	ds_read_b128 v[160:163], v151 offset:2048
	ds_read_b128 v[164:167], v151 offset:3072
	s_add_u32 s30, s28, 0xfff80080
	s_addc_u32 s31, s29, -1
	s_cmp_eq_u32 s56, 28
	s_cselect_b32 s35, s4, s31
	s_cselect_b32 s34, s7, s30
	s_cselect_b32 s31, s21, s55
	s_cselect_b32 s30, s23, s54
	v_lshl_add_u64 v[200:201], s[28:29], 0, v[136:137]
	s_add_i32 m0, s17, 0xc000
	ds_read_b128 v[168:171], v152
	ds_read_b128 v[172:175], v152 offset:1024
	ds_read_b128 v[176:179], v152 offset:2048
	ds_read_b128 v[180:183], v152 offset:3072
	ds_read_b128 v[184:187], v152 offset:4096
	ds_read_b128 v[188:191], v152 offset:5120
	ds_read_b128 v[192:195], v152 offset:6144
	ds_read_b128 v[196:199], v152 offset:7168
	global_load_lds_dwordx4 v[200:201], off
	v_lshl_add_u64 v[200:201], s[28:29], 0, v[138:139]
	s_add_i32 m0, s17, 0xe000
	s_nop 0
	global_load_lds_dwordx4 v[200:201], off
	s_waitcnt lgkmcnt(8)
	s_waitcnt vmcnt(10)
	s_barrier
	s_waitcnt lgkmcnt(0)
	s_waitcnt lgkmcnt(0)
	v_mfma_f32_16x16x32_bf16 v[124:127], v[144:147], v[168:171], v[124:127]
	v_mfma_f32_16x16x32_bf16 v[120:123], v[160:163], v[168:171], v[120:123]
	v_mfma_f32_16x16x32_bf16 v[116:119], v[144:147], v[176:179], v[116:119]
	v_mfma_f32_16x16x32_bf16 v[112:115], v[160:163], v[176:179], v[112:115]
	v_mfma_f32_16x16x32_bf16 v[100:103], v[144:147], v[184:187], v[100:103]
	v_mfma_f32_16x16x32_bf16 v[96:99], v[160:163], v[184:187], v[96:99]
	v_mfma_f32_16x16x32_bf16 v[84:87], v[144:147], v[192:195], v[84:87]
	v_mfma_f32_16x16x32_bf16 v[80:83], v[160:163], v[192:195], v[80:83]
	v_mfma_f32_16x16x32_bf16 v[124:127], v[156:159], v[172:175], v[124:127]
	v_mfma_f32_16x16x32_bf16 v[120:123], v[164:167], v[172:175], v[120:123]
	v_mfma_f32_16x16x32_bf16 v[116:119], v[156:159], v[180:183], v[116:119]
	v_mfma_f32_16x16x32_bf16 v[112:115], v[164:167], v[180:183], v[112:115]
	v_mfma_f32_16x16x32_bf16 v[100:103], v[156:159], v[188:191], v[100:103]
	v_mfma_f32_16x16x32_bf16 v[96:99], v[164:167], v[188:191], v[96:99]
	v_mfma_f32_16x16x32_bf16 v[84:87], v[156:159], v[196:199], v[84:87]
	v_mfma_f32_16x16x32_bf16 v[80:83], v[164:167], v[196:199], v[80:83]
	s_barrier
	s_add_i32 s57, s45, s33
	v_lshl_add_u64 v[218:219], s[30:31], 0, v[130:131]
	s_mov_b32 m0, s57
	ds_read_b128 v[200:203], v153
	ds_read_b128 v[204:207], v153 offset:1024
	ds_read_b128 v[210:213], v153 offset:2048
	ds_read_b128 v[214:217], v153 offset:3072
	global_load_lds_dwordx4 v[218:219], off
	v_lshl_add_u64 v[220:221], s[30:31], 0, v[134:135]
	s_add_i32 m0, s57, 0x2000
	s_nop 0
	global_load_lds_dwordx4 v[220:221], off
	s_waitcnt vmcnt(10)
	s_barrier
	s_waitcnt lgkmcnt(0)
	s_waitcnt lgkmcnt(0)
	v_mfma_f32_16x16x32_bf16 v[108:111], v[200:203], v[168:171], v[108:111]
	v_mfma_f32_16x16x32_bf16 v[104:107], v[210:213], v[168:171], v[104:107]
	v_mfma_f32_16x16x32_bf16 v[92:95], v[200:203], v[176:179], v[92:95]
	v_mfma_f32_16x16x32_bf16 v[88:91], v[210:213], v[176:179], v[88:91]
	v_mfma_f32_16x16x32_bf16 v[76:79], v[200:203], v[184:187], v[76:79]
	v_mfma_f32_16x16x32_bf16 v[72:75], v[210:213], v[184:187], v[72:75]
	v_mfma_f32_16x16x32_bf16 v[68:71], v[200:203], v[192:195], v[68:71]
	v_mfma_f32_16x16x32_bf16 v[64:67], v[210:213], v[192:195], v[64:67]
	v_mfma_f32_16x16x32_bf16 v[108:111], v[204:207], v[172:175], v[108:111]
	v_mfma_f32_16x16x32_bf16 v[104:107], v[214:217], v[172:175], v[104:107]
	v_mfma_f32_16x16x32_bf16 v[92:95], v[204:207], v[180:183], v[92:95]
	v_mfma_f32_16x16x32_bf16 v[88:91], v[214:217], v[180:183], v[88:91]
	v_mfma_f32_16x16x32_bf16 v[76:79], v[204:207], v[188:191], v[76:79]
	v_mfma_f32_16x16x32_bf16 v[72:75], v[214:217], v[188:191], v[72:75]
	v_mfma_f32_16x16x32_bf16 v[68:71], v[204:207], v[196:199], v[68:71]
	v_mfma_f32_16x16x32_bf16 v[64:67], v[214:217], v[196:199], v[64:67]
	s_mov_b32 m0, s17
	v_lshl_add_u64 v[222:223], s[34:35], 0, v[128:129]
	s_barrier
	ds_read_b128 v[168:171], v152 offset:16384
	ds_read_b128 v[172:175], v152 offset:17408
	ds_read_b128 v[176:179], v152 offset:18432
	ds_read_b128 v[180:183], v152 offset:19456
	ds_read_b128 v[184:187], v152 offset:20480
	ds_read_b128 v[188:191], v152 offset:21504
	ds_read_b128 v[192:195], v152 offset:22528
	ds_read_b128 v[196:199], v152 offset:23552
	global_load_lds_dwordx4 v[222:223], off
	v_lshl_add_u64 v[224:225], s[34:35], 0, v[132:133]
	s_mov_b32 m0, s38
	s_nop 0
	global_load_lds_dwordx4 v[224:225], off
	s_waitcnt vmcnt(10)
	s_barrier
	s_waitcnt lgkmcnt(0)
	s_waitcnt lgkmcnt(0)
	v_mfma_f32_16x16x32_bf16 v[60:63], v[144:147], v[168:171], v[60:63]
	v_mfma_f32_16x16x32_bf16 v[56:59], v[160:163], v[168:171], v[56:59]
	v_mfma_f32_16x16x32_bf16 v[52:55], v[144:147], v[176:179], v[52:55]
	v_mfma_f32_16x16x32_bf16 v[48:51], v[160:163], v[176:179], v[48:51]
	v_mfma_f32_16x16x32_bf16 v[36:39], v[144:147], v[184:187], v[36:39]
	v_mfma_f32_16x16x32_bf16 v[32:35], v[160:163], v[184:187], v[32:35]
	v_mfma_f32_16x16x32_bf16 v[20:23], v[144:147], v[192:195], v[20:23]
	v_mfma_f32_16x16x32_bf16 v[16:19], v[160:163], v[192:195], v[16:19]
	v_mfma_f32_16x16x32_bf16 v[60:63], v[156:159], v[172:175], v[60:63]
	v_mfma_f32_16x16x32_bf16 v[56:59], v[164:167], v[172:175], v[56:59]
	v_mfma_f32_16x16x32_bf16 v[52:55], v[156:159], v[180:183], v[52:55]
	v_mfma_f32_16x16x32_bf16 v[48:51], v[164:167], v[180:183], v[48:51]
	v_mfma_f32_16x16x32_bf16 v[36:39], v[156:159], v[188:191], v[36:39]
	v_mfma_f32_16x16x32_bf16 v[32:35], v[164:167], v[188:191], v[32:35]
	v_mfma_f32_16x16x32_bf16 v[20:23], v[156:159], v[196:199], v[20:23]
	v_mfma_f32_16x16x32_bf16 v[16:19], v[164:167], v[196:199], v[16:19]
	s_barrier
	s_add_u32 s60, s30, 0x80000
	s_addc_u32 s61, s31, 0
	s_add_i32 s57, s51, s33
	v_lshl_add_u64 v[144:145], s[60:61], 0, v[130:131]
	s_mov_b32 m0, s57
	s_nop 0
	global_load_lds_dwordx4 v[144:145], off
	v_lshl_add_u64 v[144:145], s[60:61], 0, v[134:135]
	s_add_i32 m0, s57, 0x2000
	s_nop 0
	global_load_lds_dwordx4 v[144:145], off
	s_waitcnt vmcnt(10)
	s_barrier
	v_mfma_f32_16x16x32_bf16 v[44:47], v[200:203], v[168:171], v[44:47]
	v_mfma_f32_16x16x32_bf16 v[40:43], v[210:213], v[168:171], v[40:43]
	v_mfma_f32_16x16x32_bf16 v[28:31], v[200:203], v[176:179], v[28:31]
	v_mfma_f32_16x16x32_bf16 v[24:27], v[210:213], v[176:179], v[24:27]
	v_mfma_f32_16x16x32_bf16 v[12:15], v[200:203], v[184:187], v[12:15]
	v_mfma_f32_16x16x32_bf16 v[8:11], v[210:213], v[184:187], v[8:11]
	v_mfma_f32_16x16x32_bf16 v[4:7], v[200:203], v[192:195], v[4:7]
	v_mfma_f32_16x16x32_bf16 v[0:3], v[210:213], v[192:195], v[0:3]
	v_mfma_f32_16x16x32_bf16 v[44:47], v[204:207], v[172:175], v[44:47]
	v_mfma_f32_16x16x32_bf16 v[40:43], v[214:217], v[172:175], v[40:43]
	v_mfma_f32_16x16x32_bf16 v[28:31], v[204:207], v[180:183], v[28:31]
	v_mfma_f32_16x16x32_bf16 v[24:27], v[214:217], v[180:183], v[24:27]
	v_mfma_f32_16x16x32_bf16 v[12:15], v[204:207], v[188:191], v[12:15]
	v_mfma_f32_16x16x32_bf16 v[8:11], v[214:217], v[188:191], v[8:11]
	v_mfma_f32_16x16x32_bf16 v[4:7], v[204:207], v[196:199], v[4:7]
	v_mfma_f32_16x16x32_bf16 v[0:3], v[214:217], v[196:199], v[0:3]
	s_add_i32 s57, 0, 0x18000
	v_add_u32_e32 v155, s57, v150
	s_barrier
	ds_read_b128 v[144:147], v155
	ds_read_b128 v[156:159], v155 offset:1024
	ds_read_b128 v[160:163], v155 offset:2048
	ds_read_b128 v[164:167], v155 offset:3072
	s_add_u32 s34, s34, 0x80000
	s_addc_u32 s35, s35, 0
	s_mov_b32 m0, s39
	v_lshl_add_u64 v[200:201], s[34:35], 0, v[128:129]
	ds_read_b128 v[168:171], v152 offset:32768
	ds_read_b128 v[172:175], v152 offset:33792
	ds_read_b128 v[176:179], v152 offset:34816
	ds_read_b128 v[180:183], v152 offset:35840
	ds_read_b128 v[184:187], v152 offset:36864
	ds_read_b128 v[188:191], v152 offset:37888
	ds_read_b128 v[192:195], v152 offset:38912
	ds_read_b128 v[196:199], v152 offset:39936
	global_load_lds_dwordx4 v[200:201], off
	v_lshl_add_u64 v[200:201], s[34:35], 0, v[132:133]
	s_mov_b32 m0, s40
	s_nop 0
	global_load_lds_dwordx4 v[200:201], off
	s_waitcnt lgkmcnt(8)
	s_waitcnt vmcnt(10)
	s_barrier
	s_waitcnt lgkmcnt(0)
	s_waitcnt lgkmcnt(0)
	v_mfma_f32_16x16x32_bf16 v[124:127], v[144:147], v[168:171], v[124:127]
	v_mfma_f32_16x16x32_bf16 v[120:123], v[160:163], v[168:171], v[120:123]
	v_mfma_f32_16x16x32_bf16 v[116:119], v[144:147], v[176:179], v[116:119]
	v_mfma_f32_16x16x32_bf16 v[112:115], v[160:163], v[176:179], v[112:115]
	v_mfma_f32_16x16x32_bf16 v[100:103], v[144:147], v[184:187], v[100:103]
	v_mfma_f32_16x16x32_bf16 v[96:99], v[160:163], v[184:187], v[96:99]
	v_mfma_f32_16x16x32_bf16 v[84:87], v[144:147], v[192:195], v[84:87]
	v_mfma_f32_16x16x32_bf16 v[80:83], v[160:163], v[192:195], v[80:83]
	v_mfma_f32_16x16x32_bf16 v[124:127], v[156:159], v[172:175], v[124:127]
	v_mfma_f32_16x16x32_bf16 v[120:123], v[164:167], v[172:175], v[120:123]
	v_mfma_f32_16x16x32_bf16 v[116:119], v[156:159], v[180:183], v[116:119]
	v_mfma_f32_16x16x32_bf16 v[112:115], v[164:167], v[180:183], v[112:115]
	v_mfma_f32_16x16x32_bf16 v[100:103], v[156:159], v[188:191], v[100:103]
	v_mfma_f32_16x16x32_bf16 v[96:99], v[164:167], v[188:191], v[96:99]
	v_mfma_f32_16x16x32_bf16 v[84:87], v[156:159], v[196:199], v[84:87]
	v_mfma_f32_16x16x32_bf16 v[80:83], v[164:167], v[196:199], v[80:83]
	s_barrier
	s_add_i32 s34, 0, 0x1c000
	s_add_i32 s35, s57, s33
	v_add_u32_e32 v155, s34, v150
	v_lshl_add_u64 v[218:219], v[218:219], 0, s[8:9]
	s_mov_b32 m0, s35
	ds_read_b128 v[200:203], v155
	ds_read_b128 v[204:207], v155 offset:1024
	ds_read_b128 v[210:213], v155 offset:2048
	ds_read_b128 v[214:217], v155 offset:3072
	global_load_lds_dwordx4 v[218:219], off
	v_lshl_add_u64 v[218:219], v[220:221], 0, s[8:9]
	s_add_i32 m0, s35, 0x2000
	s_nop 0
	global_load_lds_dwordx4 v[218:219], off
	s_waitcnt vmcnt(10)
	s_barrier
	s_waitcnt lgkmcnt(0)
	s_waitcnt lgkmcnt(0)
	v_mfma_f32_16x16x32_bf16 v[108:111], v[200:203], v[168:171], v[108:111]
	v_mfma_f32_16x16x32_bf16 v[104:107], v[210:213], v[168:171], v[104:107]
	v_mfma_f32_16x16x32_bf16 v[92:95], v[200:203], v[176:179], v[92:95]
	v_mfma_f32_16x16x32_bf16 v[88:91], v[210:213], v[176:179], v[88:91]
	v_mfma_f32_16x16x32_bf16 v[76:79], v[200:203], v[184:187], v[76:79]
	v_mfma_f32_16x16x32_bf16 v[72:75], v[210:213], v[184:187], v[72:75]
	v_mfma_f32_16x16x32_bf16 v[68:71], v[200:203], v[192:195], v[68:71]
	v_mfma_f32_16x16x32_bf16 v[64:67], v[210:213], v[192:195], v[64:67]
	v_mfma_f32_16x16x32_bf16 v[108:111], v[204:207], v[172:175], v[108:111]
	v_mfma_f32_16x16x32_bf16 v[104:107], v[214:217], v[172:175], v[104:107]
	v_mfma_f32_16x16x32_bf16 v[92:95], v[204:207], v[180:183], v[92:95]
	v_mfma_f32_16x16x32_bf16 v[88:91], v[214:217], v[180:183], v[88:91]
	v_mfma_f32_16x16x32_bf16 v[76:79], v[204:207], v[188:191], v[76:79]
	v_mfma_f32_16x16x32_bf16 v[72:75], v[214:217], v[188:191], v[72:75]
	v_mfma_f32_16x16x32_bf16 v[68:71], v[204:207], v[196:199], v[68:71]
	v_mfma_f32_16x16x32_bf16 v[64:67], v[214:217], v[196:199], v[64:67]
	s_mov_b32 m0, s43
	v_lshl_add_u64 v[218:219], v[222:223], 0, s[8:9]
	s_barrier
	ds_read_b128 v[168:171], v152 offset:49152
	ds_read_b128 v[172:175], v152 offset:50176
	ds_read_b128 v[176:179], v152 offset:51200
	ds_read_b128 v[180:183], v152 offset:52224
	ds_read_b128 v[184:187], v152 offset:53248
	ds_read_b128 v[188:191], v152 offset:54272
	ds_read_b128 v[192:195], v152 offset:55296
	ds_read_b128 v[196:199], v152 offset:56320
	global_load_lds_dwordx4 v[218:219], off
	v_lshl_add_u64 v[218:219], v[224:225], 0, s[8:9]
	s_mov_b32 m0, s44
	s_nop 0
	global_load_lds_dwordx4 v[218:219], off
	s_waitcnt vmcnt(10)
	s_barrier
	s_waitcnt lgkmcnt(0)
	s_waitcnt lgkmcnt(0)
	v_mfma_f32_16x16x32_bf16 v[60:63], v[144:147], v[168:171], v[60:63]
	v_mfma_f32_16x16x32_bf16 v[56:59], v[160:163], v[168:171], v[56:59]
	v_mfma_f32_16x16x32_bf16 v[52:55], v[144:147], v[176:179], v[52:55]
	v_mfma_f32_16x16x32_bf16 v[48:51], v[160:163], v[176:179], v[48:51]
	v_mfma_f32_16x16x32_bf16 v[36:39], v[144:147], v[184:187], v[36:39]
	v_mfma_f32_16x16x32_bf16 v[32:35], v[160:163], v[184:187], v[32:35]
	v_mfma_f32_16x16x32_bf16 v[20:23], v[144:147], v[192:195], v[20:23]
	v_mfma_f32_16x16x32_bf16 v[16:19], v[160:163], v[192:195], v[16:19]
	v_mfma_f32_16x16x32_bf16 v[60:63], v[156:159], v[172:175], v[60:63]
	v_mfma_f32_16x16x32_bf16 v[56:59], v[164:167], v[172:175], v[56:59]
	v_mfma_f32_16x16x32_bf16 v[52:55], v[156:159], v[180:183], v[52:55]
	v_mfma_f32_16x16x32_bf16 v[48:51], v[164:167], v[180:183], v[48:51]
	v_mfma_f32_16x16x32_bf16 v[36:39], v[156:159], v[188:191], v[36:39]
	v_mfma_f32_16x16x32_bf16 v[32:35], v[164:167], v[188:191], v[32:35]
	v_mfma_f32_16x16x32_bf16 v[20:23], v[156:159], v[196:199], v[20:23]
	v_mfma_f32_16x16x32_bf16 v[16:19], v[164:167], v[196:199], v[16:19]
	s_barrier
	s_add_u32 s30, s30, 0x80080
	s_addc_u32 s31, s31, 0
	s_add_i32 s34, s34, s33
	v_lshl_add_u64 v[144:145], s[30:31], 0, v[130:131]
	s_mov_b32 m0, s34
	s_nop 0
	global_load_lds_dwordx4 v[144:145], off
	v_lshl_add_u64 v[144:145], s[30:31], 0, v[134:135]
	s_add_i32 m0, s34, 0x2000
	s_nop 0
	global_load_lds_dwordx4 v[144:145], off
	s_waitcnt vmcnt(10)
	s_barrier
	v_mfma_f32_16x16x32_bf16 v[44:47], v[200:203], v[168:171], v[44:47]
	v_mfma_f32_16x16x32_bf16 v[40:43], v[210:213], v[168:171], v[40:43]
	v_mfma_f32_16x16x32_bf16 v[28:31], v[200:203], v[176:179], v[28:31]
	v_mfma_f32_16x16x32_bf16 v[24:27], v[210:213], v[176:179], v[24:27]
	v_mfma_f32_16x16x32_bf16 v[12:15], v[200:203], v[184:187], v[12:15]
	v_mfma_f32_16x16x32_bf16 v[8:11], v[210:213], v[184:187], v[8:11]
	v_mfma_f32_16x16x32_bf16 v[4:7], v[200:203], v[192:195], v[4:7]
	v_mfma_f32_16x16x32_bf16 v[0:3], v[210:213], v[192:195], v[0:3]
	v_mfma_f32_16x16x32_bf16 v[44:47], v[204:207], v[172:175], v[44:47]
	v_mfma_f32_16x16x32_bf16 v[40:43], v[214:217], v[172:175], v[40:43]
	v_mfma_f32_16x16x32_bf16 v[28:31], v[204:207], v[180:183], v[28:31]
	v_mfma_f32_16x16x32_bf16 v[24:27], v[214:217], v[180:183], v[24:27]
	v_mfma_f32_16x16x32_bf16 v[12:15], v[204:207], v[188:191], v[12:15]
	v_mfma_f32_16x16x32_bf16 v[8:11], v[214:217], v[188:191], v[8:11]
	v_mfma_f32_16x16x32_bf16 v[4:7], v[204:207], v[196:199], v[4:7]
	v_mfma_f32_16x16x32_bf16 v[0:3], v[214:217], v[196:199], v[0:3]
	s_add_i32 s56, s56, 2
	s_add_u32 s28, s28, 0x100
	s_addc_u32 s29, s29, 0
	s_add_u32 s54, s54, 0x100
	s_addc_u32 s55, s55, 0
	s_cmp_gt_u32 s56, 29
	s_barrier
	s_cbranch_scc0 .LBB0_1200
	v_mov_b32_e32 v155, v148
	v_mov_b32_e32 v156, v149
	s_cmp_gt_i32 s6, 7
	s_mov_b64 s[28:29], -1
	s_cbranch_scc0 .LBB0_1231
	s_cmp_gt_u32 s6, 15
	s_cbranch_scc0 .LBB0_1212
	s_cmp_gt_u32 s6, 23
	s_cbranch_scc0 .LBB0_1209
	s_lshl_b32 s4, s16, 8
	s_add_i32 s4, s4, s41
	v_lshl_add_u32 v144, v156, 3, s42
	v_add_u32_e32 v157, s4, v155
	v_ashrrev_i32_e32 v145, 31, v144
	v_mad_i64_i32 v[146:147], s[28:29], v157, s52, 0
	s_cmp_gt_u32 s6, 25
	s_mov_b64 s[28:29], -1
	v_lshl_add_u64 v[146:147], s[14:15], 0, v[146:147]
	v_lshlrev_b64 v[144:145], 1, v[144:145]
	v_add_u32_e32 v163, 16, v157
	v_add_u32_e32 v162, 32, v157
	v_add_u32_e32 v161, 48, v157
	v_add_u32_e32 v160, 0x80, v157
	v_add_u32_e32 v159, 0x90, v157
	v_add_u32_e32 v158, 0xa0, v157
	v_add_u32_e32 v157, 0xb0, v157
	s_cbranch_scc0 .LBB0_1206
	s_lshl_b32 s4, s6, 9
	v_lshl_add_u64 v[168:169], v[146:147], 0, s[4:5]
	v_cvt_pk_bf16_f32 v164, v124, v125
	v_cvt_pk_bf16_f32 v165, v126, v127
	v_cvt_pk_bf16_f32 v166, v120, v121
	v_cvt_pk_bf16_f32 v167, v122, v123
	v_lshl_add_u64 v[168:169], v[168:169], 0, v[144:145]
	global_store_dwordx4 v[168:169], v[164:167], off
	s_nop 1
	v_cvt_pk_bf16_f32 v164, v108, v109
	v_cvt_pk_bf16_f32 v165, v110, v111
	v_cvt_pk_bf16_f32 v166, v104, v105
	v_cvt_pk_bf16_f32 v167, v106, v107
	global_store_dwordx4 v[168:169], v[164:167], off offset:256
	v_mov_b64_e32 v[168:169], s[14:15]
	v_mad_i64_i32 v[170:171], s[28:29], v163, s52, v[168:169]
	v_lshl_add_u64 v[170:171], v[170:171], 0, s[4:5]
	v_cvt_pk_bf16_f32 v164, v116, v117
	v_cvt_pk_bf16_f32 v165, v118, v119
	v_cvt_pk_bf16_f32 v166, v112, v113
	v_cvt_pk_bf16_f32 v167, v114, v115
	v_lshl_add_u64 v[170:171], v[170:171], 0, v[144:145]
	global_store_dwordx4 v[170:171], v[164:167], off
	s_nop 1
	v_cvt_pk_bf16_f32 v164, v92, v93
	v_cvt_pk_bf16_f32 v165, v94, v95
	v_cvt_pk_bf16_f32 v166, v88, v89
	v_cvt_pk_bf16_f32 v167, v90, v91
	global_store_dwordx4 v[170:171], v[164:167], off offset:256
	v_mad_i64_i32 v[170:171], s[28:29], v162, s52, v[168:169]
	v_lshl_add_u64 v[170:171], v[170:171], 0, s[4:5]
	v_cvt_pk_bf16_f32 v164, v100, v101
	v_cvt_pk_bf16_f32 v165, v102, v103
	v_cvt_pk_bf16_f32 v166, v96, v97
	v_cvt_pk_bf16_f32 v167, v98, v99
	v_lshl_add_u64 v[170:171], v[170:171], 0, v[144:145]
	global_store_dwordx4 v[170:171], v[164:167], off
	s_nop 1
	v_cvt_pk_bf16_f32 v164, v76, v77
	v_cvt_pk_bf16_f32 v165, v78, v79
	v_cvt_pk_bf16_f32 v166, v72, v73
	v_cvt_pk_bf16_f32 v167, v74, v75
	global_store_dwordx4 v[170:171], v[164:167], off offset:256
	v_mad_i64_i32 v[170:171], s[28:29], v161, s52, v[168:169]
	v_lshl_add_u64 v[170:171], v[170:171], 0, s[4:5]
	v_cvt_pk_bf16_f32 v164, v84, v85
	v_cvt_pk_bf16_f32 v165, v86, v87
	v_cvt_pk_bf16_f32 v166, v80, v81
	v_cvt_pk_bf16_f32 v167, v82, v83
	v_lshl_add_u64 v[170:171], v[170:171], 0, v[144:145]
	global_store_dwordx4 v[170:171], v[164:167], off
	s_nop 1
	v_cvt_pk_bf16_f32 v164, v68, v69
	v_cvt_pk_bf16_f32 v165, v70, v71
	v_cvt_pk_bf16_f32 v166, v64, v65
	v_cvt_pk_bf16_f32 v167, v66, v67
	global_store_dwordx4 v[170:171], v[164:167], off offset:256
	v_mad_i64_i32 v[170:171], s[28:29], v160, s52, v[168:169]
	v_lshl_add_u64 v[170:171], v[170:171], 0, s[4:5]
	v_cvt_pk_bf16_f32 v164, v60, v61
	v_cvt_pk_bf16_f32 v165, v62, v63
	v_cvt_pk_bf16_f32 v166, v56, v57
	v_cvt_pk_bf16_f32 v167, v58, v59
	v_lshl_add_u64 v[170:171], v[170:171], 0, v[144:145]
	global_store_dwordx4 v[170:171], v[164:167], off
	s_nop 1
	v_cvt_pk_bf16_f32 v164, v44, v45
	v_cvt_pk_bf16_f32 v165, v46, v47
	v_cvt_pk_bf16_f32 v166, v40, v41
	v_cvt_pk_bf16_f32 v167, v42, v43
	global_store_dwordx4 v[170:171], v[164:167], off offset:256
	v_mad_i64_i32 v[170:171], s[28:29], v159, s52, v[168:169]
	v_lshl_add_u64 v[170:171], v[170:171], 0, s[4:5]
	v_cvt_pk_bf16_f32 v164, v52, v53
	v_cvt_pk_bf16_f32 v165, v54, v55
	v_cvt_pk_bf16_f32 v166, v48, v49
	v_cvt_pk_bf16_f32 v167, v50, v51
	v_lshl_add_u64 v[170:171], v[170:171], 0, v[144:145]
	global_store_dwordx4 v[170:171], v[164:167], off
	s_nop 1
	v_cvt_pk_bf16_f32 v164, v28, v29
	v_cvt_pk_bf16_f32 v165, v30, v31
	v_cvt_pk_bf16_f32 v166, v24, v25
	v_cvt_pk_bf16_f32 v167, v26, v27
	global_store_dwordx4 v[170:171], v[164:167], off offset:256
	v_mad_i64_i32 v[170:171], s[28:29], v158, s52, v[168:169]
	v_lshl_add_u64 v[170:171], v[170:171], 0, s[4:5]
	v_cvt_pk_bf16_f32 v164, v36, v37
	v_cvt_pk_bf16_f32 v165, v38, v39
	v_cvt_pk_bf16_f32 v166, v32, v33
	v_cvt_pk_bf16_f32 v167, v34, v35
	v_lshl_add_u64 v[170:171], v[170:171], 0, v[144:145]
	v_mad_i64_i32 v[168:169], s[28:29], v157, s52, v[168:169]
	global_store_dwordx4 v[170:171], v[164:167], off
	v_lshl_add_u64 v[168:169], v[168:169], 0, s[4:5]
	v_lshl_add_u64 v[168:169], v[168:169], 0, v[144:145]
	v_cvt_pk_bf16_f32 v164, v12, v13
	v_cvt_pk_bf16_f32 v165, v14, v15
	v_cvt_pk_bf16_f32 v166, v8, v9
	v_cvt_pk_bf16_f32 v167, v10, v11
	global_store_dwordx4 v[170:171], v[164:167], off offset:256
	s_mov_b64 s[28:29], 0
	s_nop 0
	v_cvt_pk_bf16_f32 v164, v20, v21
	v_cvt_pk_bf16_f32 v165, v22, v23
	v_cvt_pk_bf16_f32 v166, v16, v17
	v_cvt_pk_bf16_f32 v167, v18, v19
	global_store_dwordx4 v[168:169], v[164:167], off
	s_nop 1
	v_cvt_pk_bf16_f32 v164, v4, v5
	v_cvt_pk_bf16_f32 v165, v6, v7
	v_cvt_pk_bf16_f32 v166, v0, v1
	v_cvt_pk_bf16_f32 v167, v2, v3
	global_store_dwordx4 v[168:169], v[164:167], off offset:256

.LBB0_1402:
	ds_read_b128 v[150:153], v147
	ds_read_b128 v[154:157], v147 offset:1024
	ds_read_b128 v[158:161], v147 offset:2048
	ds_read_b128 v[162:165], v147 offset:3072
	s_add_u32 s34, s30, 0x100
	s_addc_u32 s35, s31, 0
	s_cmp_eq_u32 s69, 36
	s_cselect_b32 s39, s5, s35
	s_cselect_b32 s38, s4, s34
	s_cselect_b32 s37, s7, s68
	s_cselect_b32 s36, s6, s67
	v_lshl_add_u64 v[198:199], s[30:31], 0, v[136:137]
	s_add_i32 m0, s41, 0xc000
	ds_read_b128 v[166:169], v148
	ds_read_b128 v[170:173], v148 offset:1024
	ds_read_b128 v[174:177], v148 offset:2048
	ds_read_b128 v[178:181], v148 offset:3072
	ds_read_b128 v[182:185], v148 offset:4096
	ds_read_b128 v[186:189], v148 offset:5120
	ds_read_b128 v[190:193], v148 offset:6144
	ds_read_b128 v[194:197], v148 offset:7168
	global_load_lds_dwordx4 v[198:199], off
	v_lshl_add_u64 v[198:199], s[30:31], 0, v[138:139]
	s_add_i32 m0, s41, 0xe000
	s_nop 0
	global_load_lds_dwordx4 v[198:199], off
	s_waitcnt lgkmcnt(8)
	s_waitcnt vmcnt(10)
	s_barrier
	s_waitcnt lgkmcnt(0)
	s_waitcnt lgkmcnt(0)
	v_mfma_f32_16x16x32_bf16 v[124:127], v[150:153], v[166:169], v[124:127]
	v_mfma_f32_16x16x32_bf16 v[120:123], v[158:161], v[166:169], v[120:123]
	v_mfma_f32_16x16x32_bf16 v[116:119], v[150:153], v[174:177], v[116:119]
	v_mfma_f32_16x16x32_bf16 v[112:115], v[158:161], v[174:177], v[112:115]
	v_mfma_f32_16x16x32_bf16 v[100:103], v[150:153], v[182:185], v[100:103]
	v_mfma_f32_16x16x32_bf16 v[96:99], v[158:161], v[182:185], v[96:99]
	v_mfma_f32_16x16x32_bf16 v[84:87], v[150:153], v[190:193], v[84:87]
	v_mfma_f32_16x16x32_bf16 v[80:83], v[158:161], v[190:193], v[80:83]
	v_mfma_f32_16x16x32_bf16 v[124:127], v[154:157], v[170:173], v[124:127]
	v_mfma_f32_16x16x32_bf16 v[120:123], v[162:165], v[170:173], v[120:123]
	v_mfma_f32_16x16x32_bf16 v[116:119], v[154:157], v[178:181], v[116:119]
	v_mfma_f32_16x16x32_bf16 v[112:115], v[162:165], v[178:181], v[112:115]
	v_mfma_f32_16x16x32_bf16 v[100:103], v[154:157], v[186:189], v[100:103]
	v_mfma_f32_16x16x32_bf16 v[96:99], v[162:165], v[186:189], v[96:99]
	v_mfma_f32_16x16x32_bf16 v[84:87], v[154:157], v[194:197], v[84:87]
	v_mfma_f32_16x16x32_bf16 v[80:83], v[162:165], v[194:197], v[80:83]
	s_barrier
	s_add_i32 s30, s54, s40
	v_lshl_add_u64 v[206:207], s[36:37], 0, v[130:131]
	s_mov_b32 m0, s30
	ds_read_b128 v[198:201], v149
	ds_read_b128 v[202:205], v149 offset:1024
	ds_read_b128 v[210:213], v149 offset:2048
	ds_read_b128 v[214:217], v149 offset:3072
	global_load_lds_dwordx4 v[206:207], off
	v_lshl_add_u64 v[218:219], s[36:37], 0, v[134:135]
	s_add_i32 m0, s30, 0x2000
	s_nop 0
	global_load_lds_dwordx4 v[218:219], off
	s_waitcnt vmcnt(10)
	s_barrier
	s_waitcnt lgkmcnt(0)
	s_waitcnt lgkmcnt(0)
	v_mfma_f32_16x16x32_bf16 v[108:111], v[198:201], v[166:169], v[108:111]
	v_mfma_f32_16x16x32_bf16 v[104:107], v[210:213], v[166:169], v[104:107]
	v_mfma_f32_16x16x32_bf16 v[92:95], v[198:201], v[174:177], v[92:95]
	v_mfma_f32_16x16x32_bf16 v[88:91], v[210:213], v[174:177], v[88:91]
	v_mfma_f32_16x16x32_bf16 v[76:79], v[198:201], v[182:185], v[76:79]
	v_mfma_f32_16x16x32_bf16 v[72:75], v[210:213], v[182:185], v[72:75]
	v_mfma_f32_16x16x32_bf16 v[68:71], v[198:201], v[190:193], v[68:71]
	v_mfma_f32_16x16x32_bf16 v[64:67], v[210:213], v[190:193], v[64:67]
	v_mfma_f32_16x16x32_bf16 v[108:111], v[202:205], v[170:173], v[108:111]
	v_mfma_f32_16x16x32_bf16 v[104:107], v[214:217], v[170:173], v[104:107]
	v_mfma_f32_16x16x32_bf16 v[92:95], v[202:205], v[178:181], v[92:95]
	v_mfma_f32_16x16x32_bf16 v[88:91], v[214:217], v[178:181], v[88:91]
	v_mfma_f32_16x16x32_bf16 v[76:79], v[202:205], v[186:189], v[76:79]
	v_mfma_f32_16x16x32_bf16 v[72:75], v[214:217], v[186:189], v[72:75]
	v_mfma_f32_16x16x32_bf16 v[68:71], v[202:205], v[194:197], v[68:71]
	v_mfma_f32_16x16x32_bf16 v[64:67], v[214:217], v[194:197], v[64:67]
	s_mov_b32 m0, s41
	v_lshl_add_u64 v[220:221], s[38:39], 0, v[128:129]
	s_barrier
	ds_read_b128 v[166:169], v148 offset:16384
	ds_read_b128 v[170:173], v148 offset:17408
	ds_read_b128 v[174:177], v148 offset:18432
	ds_read_b128 v[178:181], v148 offset:19456
	ds_read_b128 v[182:185], v148 offset:20480
	ds_read_b128 v[186:189], v148 offset:21504
	ds_read_b128 v[190:193], v148 offset:22528
	ds_read_b128 v[194:197], v148 offset:23552
	global_load_lds_dwordx4 v[220:221], off
	v_lshl_add_u64 v[222:223], s[38:39], 0, v[132:133]
	s_mov_b32 m0, s42
	s_nop 0
	global_load_lds_dwordx4 v[222:223], off
	s_waitcnt vmcnt(10)
	s_barrier
	s_waitcnt lgkmcnt(0)
	s_waitcnt lgkmcnt(0)
	v_mfma_f32_16x16x32_bf16 v[60:63], v[150:153], v[166:169], v[60:63]
	v_mfma_f32_16x16x32_bf16 v[56:59], v[158:161], v[166:169], v[56:59]
	v_mfma_f32_16x16x32_bf16 v[52:55], v[150:153], v[174:177], v[52:55]
	v_mfma_f32_16x16x32_bf16 v[48:51], v[158:161], v[174:177], v[48:51]
	v_mfma_f32_16x16x32_bf16 v[36:39], v[150:153], v[182:185], v[36:39]
	v_mfma_f32_16x16x32_bf16 v[32:35], v[158:161], v[182:185], v[32:35]
	v_mfma_f32_16x16x32_bf16 v[20:23], v[150:153], v[190:193], v[20:23]
	v_mfma_f32_16x16x32_bf16 v[16:19], v[158:161], v[190:193], v[16:19]
	v_mfma_f32_16x16x32_bf16 v[60:63], v[154:157], v[170:173], v[60:63]
	v_mfma_f32_16x16x32_bf16 v[56:59], v[162:165], v[170:173], v[56:59]
	v_mfma_f32_16x16x32_bf16 v[52:55], v[154:157], v[178:181], v[52:55]
	v_mfma_f32_16x16x32_bf16 v[48:51], v[162:165], v[178:181], v[48:51]
	v_mfma_f32_16x16x32_bf16 v[36:39], v[154:157], v[186:189], v[36:39]
	v_mfma_f32_16x16x32_bf16 v[32:35], v[162:165], v[186:189], v[32:35]
	v_mfma_f32_16x16x32_bf16 v[20:23], v[154:157], v[194:197], v[20:23]
	v_mfma_f32_16x16x32_bf16 v[16:19], v[162:165], v[194:197], v[16:19]
	s_barrier
	s_add_u32 s30, s36, 0xa0000
	s_addc_u32 s31, s37, 0
	s_add_i32 s70, s55, s40
	v_lshl_add_u64 v[150:151], s[30:31], 0, v[130:131]
	s_mov_b32 m0, s70
	s_nop 0
	global_load_lds_dwordx4 v[150:151], off
	v_lshl_add_u64 v[150:151], s[30:31], 0, v[134:135]
	s_add_i32 m0, s70, 0x2000
	s_nop 0
	global_load_lds_dwordx4 v[150:151], off
	s_waitcnt vmcnt(10)
	s_barrier
	v_mfma_f32_16x16x32_bf16 v[44:47], v[198:201], v[166:169], v[44:47]
	v_mfma_f32_16x16x32_bf16 v[40:43], v[210:213], v[166:169], v[40:43]
	v_mfma_f32_16x16x32_bf16 v[28:31], v[198:201], v[174:177], v[28:31]
	v_mfma_f32_16x16x32_bf16 v[24:27], v[210:213], v[174:177], v[24:27]
	v_mfma_f32_16x16x32_bf16 v[12:15], v[198:201], v[182:185], v[12:15]
	v_mfma_f32_16x16x32_bf16 v[8:11], v[210:213], v[182:185], v[8:11]
	v_mfma_f32_16x16x32_bf16 v[4:7], v[198:201], v[190:193], v[4:7]
	v_mfma_f32_16x16x32_bf16 v[0:3], v[210:213], v[190:193], v[0:3]
	v_mfma_f32_16x16x32_bf16 v[44:47], v[202:205], v[170:173], v[44:47]
	v_mfma_f32_16x16x32_bf16 v[40:43], v[214:217], v[170:173], v[40:43]
	v_mfma_f32_16x16x32_bf16 v[28:31], v[202:205], v[178:181], v[28:31]
	v_mfma_f32_16x16x32_bf16 v[24:27], v[214:217], v[178:181], v[24:27]
	v_mfma_f32_16x16x32_bf16 v[12:15], v[202:205], v[186:189], v[12:15]
	v_mfma_f32_16x16x32_bf16 v[8:11], v[214:217], v[186:189], v[8:11]
	v_mfma_f32_16x16x32_bf16 v[4:7], v[202:205], v[194:197], v[4:7]
	v_mfma_f32_16x16x32_bf16 v[0:3], v[214:217], v[194:197], v[0:3]
	s_add_i32 s70, 0, 0x18000
	v_add_u32_e32 v162, s70, v146
	s_barrier
	ds_read_b128 v[150:153], v162
	ds_read_b128 v[154:157], v162 offset:1024
	ds_read_b128 v[158:161], v162 offset:2048
	ds_read_b128 v[162:165], v162 offset:3072
	s_add_u32 s30, s38, 0xa0000
	s_addc_u32 s31, s39, 0
	s_mov_b32 m0, s43
	v_lshl_add_u64 v[198:199], s[30:31], 0, v[128:129]
	ds_read_b128 v[166:169], v148 offset:32768
	ds_read_b128 v[170:173], v148 offset:33792
	ds_read_b128 v[174:177], v148 offset:34816
	ds_read_b128 v[178:181], v148 offset:35840
	ds_read_b128 v[182:185], v148 offset:36864
	ds_read_b128 v[186:189], v148 offset:37888
	ds_read_b128 v[190:193], v148 offset:38912
	ds_read_b128 v[194:197], v148 offset:39936
	global_load_lds_dwordx4 v[198:199], off
	v_lshl_add_u64 v[198:199], s[30:31], 0, v[132:133]
	s_mov_b32 m0, s44
	s_nop 0
	global_load_lds_dwordx4 v[198:199], off
	s_waitcnt lgkmcnt(8)
	s_waitcnt vmcnt(10)
	s_barrier
	s_waitcnt lgkmcnt(0)
	s_waitcnt lgkmcnt(0)
	v_mfma_f32_16x16x32_bf16 v[124:127], v[150:153], v[166:169], v[124:127]
	v_mfma_f32_16x16x32_bf16 v[120:123], v[158:161], v[166:169], v[120:123]
	v_mfma_f32_16x16x32_bf16 v[116:119], v[150:153], v[174:177], v[116:119]
	v_mfma_f32_16x16x32_bf16 v[112:115], v[158:161], v[174:177], v[112:115]
	v_mfma_f32_16x16x32_bf16 v[100:103], v[150:153], v[182:185], v[100:103]
	v_mfma_f32_16x16x32_bf16 v[96:99], v[158:161], v[182:185], v[96:99]
	v_mfma_f32_16x16x32_bf16 v[84:87], v[150:153], v[190:193], v[84:87]
	v_mfma_f32_16x16x32_bf16 v[80:83], v[158:161], v[190:193], v[80:83]
	v_mfma_f32_16x16x32_bf16 v[124:127], v[154:157], v[170:173], v[124:127]
	v_mfma_f32_16x16x32_bf16 v[120:123], v[162:165], v[170:173], v[120:123]
	v_mfma_f32_16x16x32_bf16 v[116:119], v[154:157], v[178:181], v[116:119]
	v_mfma_f32_16x16x32_bf16 v[112:115], v[162:165], v[178:181], v[112:115]
	v_mfma_f32_16x16x32_bf16 v[100:103], v[154:157], v[186:189], v[100:103]
	v_mfma_f32_16x16x32_bf16 v[96:99], v[162:165], v[186:189], v[96:99]
	v_mfma_f32_16x16x32_bf16 v[84:87], v[154:157], v[194:197], v[84:87]
	v_mfma_f32_16x16x32_bf16 v[80:83], v[162:165], v[194:197], v[80:83]
	s_barrier
	s_add_i32 s38, 0, 0x1c000
	s_add_i32 s30, s70, s40
	v_add_u32_e32 v214, s38, v146
	v_lshl_add_u64 v[206:207], v[206:207], 0, s[14:15]
	s_mov_b32 m0, s30
	ds_read_b128 v[198:201], v214
	ds_read_b128 v[202:205], v214 offset:1024
	ds_read_b128 v[210:213], v214 offset:2048
	ds_read_b128 v[214:217], v214 offset:3072
	global_load_lds_dwordx4 v[206:207], off
	v_lshl_add_u64 v[206:207], v[218:219], 0, s[14:15]
	s_add_i32 m0, s30, 0x2000
	s_nop 0
	global_load_lds_dwordx4 v[206:207], off
	s_waitcnt vmcnt(10)
	s_barrier
	s_waitcnt lgkmcnt(0)
	s_waitcnt lgkmcnt(0)
	v_mfma_f32_16x16x32_bf16 v[108:111], v[198:201], v[166:169], v[108:111]
	v_mfma_f32_16x16x32_bf16 v[104:107], v[210:213], v[166:169], v[104:107]
	v_mfma_f32_16x16x32_bf16 v[92:95], v[198:201], v[174:177], v[92:95]
	v_mfma_f32_16x16x32_bf16 v[88:91], v[210:213], v[174:177], v[88:91]
	v_mfma_f32_16x16x32_bf16 v[76:79], v[198:201], v[182:185], v[76:79]
	v_mfma_f32_16x16x32_bf16 v[72:75], v[210:213], v[182:185], v[72:75]
	v_mfma_f32_16x16x32_bf16 v[68:71], v[198:201], v[190:193], v[68:71]
	v_mfma_f32_16x16x32_bf16 v[64:67], v[210:213], v[190:193], v[64:67]
	v_mfma_f32_16x16x32_bf16 v[108:111], v[202:205], v[170:173], v[108:111]
	v_mfma_f32_16x16x32_bf16 v[104:107], v[214:217], v[170:173], v[104:107]
	v_mfma_f32_16x16x32_bf16 v[92:95], v[202:205], v[178:181], v[92:95]
	v_mfma_f32_16x16x32_bf16 v[88:91], v[214:217], v[178:181], v[88:91]
	v_mfma_f32_16x16x32_bf16 v[76:79], v[202:205], v[186:189], v[76:79]
	v_mfma_f32_16x16x32_bf16 v[72:75], v[214:217], v[186:189], v[72:75]
	v_mfma_f32_16x16x32_bf16 v[68:71], v[202:205], v[194:197], v[68:71]
	v_mfma_f32_16x16x32_bf16 v[64:67], v[214:217], v[194:197], v[64:67]
	s_mov_b32 m0, s52
	v_lshl_add_u64 v[206:207], v[220:221], 0, s[14:15]
	s_barrier
	ds_read_b128 v[166:169], v148 offset:49152
	ds_read_b128 v[170:173], v148 offset:50176
	ds_read_b128 v[174:177], v148 offset:51200
	ds_read_b128 v[178:181], v148 offset:52224
	ds_read_b128 v[182:185], v148 offset:53248
	ds_read_b128 v[186:189], v148 offset:54272
	ds_read_b128 v[190:193], v148 offset:55296
	ds_read_b128 v[194:197], v148 offset:56320
	global_load_lds_dwordx4 v[206:207], off
	v_lshl_add_u64 v[206:207], v[222:223], 0, s[14:15]
	s_mov_b32 m0, s53
	s_nop 0
	global_load_lds_dwordx4 v[206:207], off
	s_waitcnt vmcnt(10)
	s_barrier
	s_waitcnt lgkmcnt(0)
	s_waitcnt lgkmcnt(0)
	v_mfma_f32_16x16x32_bf16 v[60:63], v[150:153], v[166:169], v[60:63]
	v_mfma_f32_16x16x32_bf16 v[56:59], v[158:161], v[166:169], v[56:59]
	v_mfma_f32_16x16x32_bf16 v[52:55], v[150:153], v[174:177], v[52:55]
	v_mfma_f32_16x16x32_bf16 v[48:51], v[158:161], v[174:177], v[48:51]
	v_mfma_f32_16x16x32_bf16 v[36:39], v[150:153], v[182:185], v[36:39]
	v_mfma_f32_16x16x32_bf16 v[32:35], v[158:161], v[182:185], v[32:35]
	v_mfma_f32_16x16x32_bf16 v[20:23], v[150:153], v[190:193], v[20:23]
	v_mfma_f32_16x16x32_bf16 v[16:19], v[158:161], v[190:193], v[16:19]
	v_mfma_f32_16x16x32_bf16 v[60:63], v[154:157], v[170:173], v[60:63]
	v_mfma_f32_16x16x32_bf16 v[56:59], v[162:165], v[170:173], v[56:59]
	v_mfma_f32_16x16x32_bf16 v[52:55], v[154:157], v[178:181], v[52:55]
	v_mfma_f32_16x16x32_bf16 v[48:51], v[162:165], v[178:181], v[48:51]
	v_mfma_f32_16x16x32_bf16 v[36:39], v[154:157], v[186:189], v[36:39]
	v_mfma_f32_16x16x32_bf16 v[32:35], v[162:165], v[186:189], v[32:35]
	v_mfma_f32_16x16x32_bf16 v[20:23], v[154:157], v[194:197], v[20:23]
	v_mfma_f32_16x16x32_bf16 v[16:19], v[162:165], v[194:197], v[16:19]
	s_barrier
	s_add_u32 s30, s36, 0xa0080
	s_addc_u32 s31, s37, 0
	s_add_i32 s36, s38, s40
	v_lshl_add_u64 v[150:151], s[30:31], 0, v[130:131]
	s_mov_b32 m0, s36
	s_nop 0
	global_load_lds_dwordx4 v[150:151], off
	v_lshl_add_u64 v[150:151], s[30:31], 0, v[134:135]
	s_add_i32 m0, s36, 0x2000
	s_nop 0
	global_load_lds_dwordx4 v[150:151], off
	s_waitcnt vmcnt(10)
	s_barrier
	v_mfma_f32_16x16x32_bf16 v[44:47], v[198:201], v[166:169], v[44:47]
	v_mfma_f32_16x16x32_bf16 v[40:43], v[210:213], v[166:169], v[40:43]
	v_mfma_f32_16x16x32_bf16 v[28:31], v[198:201], v[174:177], v[28:31]
	v_mfma_f32_16x16x32_bf16 v[24:27], v[210:213], v[174:177], v[24:27]
	v_mfma_f32_16x16x32_bf16 v[12:15], v[198:201], v[182:185], v[12:15]
	v_mfma_f32_16x16x32_bf16 v[8:11], v[210:213], v[182:185], v[8:11]
	v_mfma_f32_16x16x32_bf16 v[4:7], v[198:201], v[190:193], v[4:7]
	v_mfma_f32_16x16x32_bf16 v[0:3], v[210:213], v[190:193], v[0:3]
	v_mfma_f32_16x16x32_bf16 v[44:47], v[202:205], v[170:173], v[44:47]
	v_mfma_f32_16x16x32_bf16 v[40:43], v[214:217], v[170:173], v[40:43]
	v_mfma_f32_16x16x32_bf16 v[28:31], v[202:205], v[178:181], v[28:31]
	v_mfma_f32_16x16x32_bf16 v[24:27], v[214:217], v[178:181], v[24:27]
	v_mfma_f32_16x16x32_bf16 v[12:15], v[202:205], v[186:189], v[12:15]
	v_mfma_f32_16x16x32_bf16 v[8:11], v[214:217], v[186:189], v[8:11]
	v_mfma_f32_16x16x32_bf16 v[4:7], v[202:205], v[194:197], v[4:7]
	v_mfma_f32_16x16x32_bf16 v[0:3], v[214:217], v[194:197], v[0:3]
	s_add_i32 s69, s69, 2
	s_add_u32 s67, s67, 0x100
	s_addc_u32 s68, s68, 0
	s_cmp_gt_u32 s69, 37
	s_mov_b64 s[30:31], s[34:35]
	s_barrier
	s_cbranch_scc0 .LBB0_1402
	v_mov_b32_e32 v150, v145
	v_mov_b32_e32 v151, v144
	s_lshl_b32 s30, s63, 8
	s_add_i32 s30, s30, s49
	v_add_u32_e32 v150, s30, v150
	s_lshl_b32 s30, s66, 8
	s_or_b32 s30, s30, s51
	v_lshl_add_u32 v152, v151, 3, s30
	v_ashrrev_i32_e32 v151, 31, v150
	v_lshlrev_b64 v[150:151], 12, v[150:151]
	v_ashrrev_i32_e32 v153, 31, v152
	v_lshl_add_u64 v[150:151], s[10:11], 0, v[150:151]
	v_lshl_add_u64 v[150:151], v[152:153], 1, v[150:151]
	v_cvt_pk_bf16_f32 v108, v108, v109
	v_cvt_pk_bf16_f32 v109, v110, v111
	v_cvt_pk_bf16_f32 v110, v104, v105
	v_cvt_pk_bf16_f32 v111, v106, v107
	global_store_dwordx4 v[150:151], v[108:111], off offset:256
	v_cvt_pk_bf16_f32 v92, v92, v93
	v_cvt_pk_bf16_f32 v93, v94, v95
	v_add_co_u32_e32 v110, vcc, s48, v150
	v_lshl_add_u64 v[108:109], v[150:151], 0, s[18:19]
	s_nop 0
	v_addc_co_u32_e32 v111, vcc, 0, v151, vcc
	v_cvt_pk_bf16_f32 v94, v88, v89
	v_cvt_pk_bf16_f32 v95, v90, v91
	global_store_dwordx4 v[108:109], v[92:95], off offset:256
	v_cvt_pk_bf16_f32 v76, v76, v77
	v_cvt_pk_bf16_f32 v77, v78, v79
	v_add_co_u32_e32 v94, vcc, s56, v150
	v_lshl_add_u64 v[92:93], v[150:151], 0, s[20:21]
	s_nop 0
	v_addc_co_u32_e32 v95, vcc, 0, v151, vcc
	v_cvt_pk_bf16_f32 v78, v72, v73
	v_cvt_pk_bf16_f32 v79, v74, v75
	global_store_dwordx4 v[92:93], v[76:79], off offset:256
	v_cvt_pk_bf16_f32 v60, v60, v61
	v_cvt_pk_bf16_f32 v61, v62, v63
	v_add_co_u32_e32 v78, vcc, s57, v150
	v_cvt_pk_bf16_f32 v62, v56, v57
	s_nop 0
	v_addc_co_u32_e32 v79, vcc, 0, v151, vcc
	v_add_co_u32_e32 v56, vcc, s59, v150
	v_cvt_pk_bf16_f32 v68, v68, v69
	v_cvt_pk_bf16_f32 v69, v70, v71
	v_cvt_pk_bf16_f32 v70, v64, v65
	v_lshl_add_u64 v[64:65], v[150:151], 0, s[24:25]
	v_addc_co_u32_e32 v57, vcc, 0, v151, vcc
	v_cvt_pk_bf16_f32 v44, v44, v45
	v_cvt_pk_bf16_f32 v45, v46, v47
	v_cvt_pk_bf16_f32 v46, v40, v41
	v_cvt_pk_bf16_f32 v47, v42, v43
	global_store_dwordx4 v[64:65], v[44:47], off offset:256
	v_cvt_pk_bf16_f32 v28, v28, v29
	v_cvt_pk_bf16_f32 v29, v30, v31
	v_add_co_u32_e32 v46, vcc, s60, v150
	v_lshl_add_u64 v[44:45], v[150:151], 0, s[26:27]
	s_nop 0
	v_addc_co_u32_e32 v47, vcc, 0, v151, vcc
	v_cvt_pk_bf16_f32 v30, v24, v25
	v_cvt_pk_bf16_f32 v31, v26, v27
	global_store_dwordx4 v[44:45], v[28:31], off offset:256
	v_cvt_pk_bf16_f32 v12, v12, v13
	v_cvt_pk_bf16_f32 v13, v14, v15
	v_add_co_u32_e32 v30, vcc, s61, v150
	v_lshl_add_u64 v[28:29], v[150:151], 0, s[8:9]
	s_nop 0
	v_addc_co_u32_e32 v31, vcc, 0, v151, vcc
	v_cvt_pk_bf16_f32 v14, v8, v9
	v_cvt_pk_bf16_f32 v15, v10, v11
	global_store_dwordx4 v[28:29], v[12:15], off offset:256
	v_cvt_pk_bf16_f32 v124, v124, v125
	v_cvt_pk_bf16_f32 v125, v126, v127
	v_add_co_u32_e32 v14, vcc, s62, v150
	v_cvt_pk_bf16_f32 v126, v120, v121
	s_nop 0
	v_addc_co_u32_e32 v15, vcc, 0, v151, vcc
	v_cvt_pk_bf16_f32 v127, v122, v123
	v_cvt_pk_bf16_f32 v104, v116, v117
	v_cvt_pk_bf16_f32 v105, v118, v119
	v_cvt_pk_bf16_f32 v106, v112, v113
	v_cvt_pk_bf16_f32 v107, v114, v115
	v_cvt_pk_bf16_f32 v88, v100, v101
	v_cvt_pk_bf16_f32 v89, v102, v103
	v_cvt_pk_bf16_f32 v90, v96, v97
	v_cvt_pk_bf16_f32 v91, v98, v99
	v_lshl_add_u64 v[76:77], v[150:151], 0, s[22:23]
	v_cvt_pk_bf16_f32 v72, v84, v85
	v_cvt_pk_bf16_f32 v73, v86, v87
	v_cvt_pk_bf16_f32 v74, v80, v81
	v_cvt_pk_bf16_f32 v75, v82, v83
	v_cvt_pk_bf16_f32 v71, v66, v67
	v_cvt_pk_bf16_f32 v63, v58, v59
	v_cvt_pk_bf16_f32 v40, v52, v53
	v_cvt_pk_bf16_f32 v41, v54, v55
	v_cvt_pk_bf16_f32 v42, v48, v49
	v_cvt_pk_bf16_f32 v43, v50, v51
	v_cvt_pk_bf16_f32 v24, v36, v37
	v_cvt_pk_bf16_f32 v25, v38, v39
	v_cvt_pk_bf16_f32 v26, v32, v33
	v_cvt_pk_bf16_f32 v27, v34, v35
	v_lshl_add_u64 v[12:13], v[150:151], 0, s[28:29]
	v_cvt_pk_bf16_f32 v8, v20, v21
	v_cvt_pk_bf16_f32 v9, v22, v23
	v_cvt_pk_bf16_f32 v10, v16, v17
	v_cvt_pk_bf16_f32 v11, v18, v19
	v_cvt_pk_bf16_f32 v4, v4, v5
	v_cvt_pk_bf16_f32 v5, v6, v7
	v_cvt_pk_bf16_f32 v6, v0, v1
	v_cvt_pk_bf16_f32 v7, v2, v3
	s_and_b64 vcc, exec, s[2:3]
	s_mov_b32 s66, s64
	s_mov_b32 s63, s65
	s_mov_b64 s[34:35], s[6:7]
	s_mov_b64 s[30:31], s[4:5]
	global_store_dwordx4 v[150:151], v[124:127], off
	global_store_dwordx4 v[110:111], v[104:107], off
	global_store_dwordx4 v[94:95], v[88:91], off
	global_store_dwordx4 v[78:79], v[72:75], off
	global_store_dwordx4 v[76:77], v[68:71], off offset:256
	global_store_dwordx4 v[56:57], v[60:63], off
	global_store_dwordx4 v[46:47], v[40:43], off
	global_store_dwordx4 v[30:31], v[24:27], off
	global_store_dwordx4 v[14:15], v[8:11], off
	global_store_dwordx4 v[12:13], v[4:7], off offset:256
	s_cbranch_vccz .LBB0_1391
	s_waitcnt vmcnt(0)
	s_cmpk_gt_u32 s33, 0xff
	s_cbranch_scc1 .LBB0_1406
	s_barrier
